# attention PV: counted waits also in the final 4-MFMA group of each tile
# baseline (speedup 1.0000x reference)
; #define SBAR() __builtin_amdgcn_sched_barrier(0)
; __device__ __forceinline__ void finishSM(f32x16& p0, f32x16& p1, float alpha, float& l_reg, bf16x8& pa0, bf16x8& pa1, bf16x8& pa2, bf16x8& pa3) {
; #pragma unroll
;   for (int r = 0; r < 16; ++r) p1[r] = __builtin_amdgcn_exp2f(p1[r]);
;   float ps = 0;
; #pragma unroll
;   for (int r = 0; r < 16; ++r) ps += p0[r];
; #pragma unroll
;   for (int r = 0; r < 16; ++r) ps += p1[r];
;   { auto rr = __builtin_amdgcn_permlane32_swap(__float_as_uint(ps), __float_as_uint(ps), false, false);
;     ps = __uint_as_float(rr[0]) + __uint_as_float(rr[1]); }
;   l_reg = l_reg * alpha + ps;
;     ...
;   PK4(p0, 0, pa0); PK4(p0, 8, pa1); PK4(p1, 0, pa2); PK4(p1, 8, pa3);
; template <int D0> __device__ __forceinline__ void pv_one(f32x16& od, int vb, bf16x8 pa0, bf16x8 pa1, bf16x8 pa2, bf16x8 pa3) {
;   const s16x4 l0 = tr_read<v_rd_off(D0, 0, 0)>(vb), h0 = tr_read<v_rd_off(D0, 0, 1)>(vb), l1 = tr_read<v_rd_off(D0, 1, 0)>(vb), h1 = tr_read<v_rd_off(D0, 1, 1)>(vb);
;   const s16x4 l2 = tr_read<v_rd_off(D0, 2, 0)>(vb), h2 = tr_read<v_rd_off(D0, 2, 1)>(vb), l3 = tr_read<v_rd_off(D0, 3, 0)>(vb), h3 = tr_read<v_rd_off(D0, 3, 1)>(vb);
;   asm volatile("s_waitcnt lgkmcnt(0)" ::: "memory"); SBAR();
;     ...
;   od = __builtin_amdgcn_mfma_f32_32x32x16_bf16(pa0, PK(l0, h0), od, 0, 0, 0);
;   od = __builtin_amdgcn_mfma_f32_32x32x16_bf16(pa1, PK(l1, h1), od, 0, 0, 0);
;   od = __builtin_amdgcn_mfma_f32_32x32x16_bf16(pa2, PK(l2, h2), od, 0, 0, 0);
;   od = __builtin_amdgcn_mfma_f32_32x32x16_bf16(pa3, PK(l3, h3), od, 0, 0, 0);
;     ...
; }
; __device__ __forceinline__ void pv_d0(f32x16* o, int vb, bf16x8 pa0, bf16x8 pa1, bf16x8 pa2, bf16x8 pa3) {
;   pv_one<0>(o[0], vb, pa0, pa1, pa2, pa3); pv_one<1>(o[1], vb, pa0, pa1, pa2, pa3); pv_one<2>(o[2], vb, pa0, pa1, pa2, pa3); pv_one<3>(o[3], vb, pa0, pa1, pa2, pa3);
.LBB0_513:
	s_or_b64 exec, exec, s[36:37]
	v_add_f32_e32 v2, 0, v94
	v_add_f32_e32 v2, v95, v2
	v_add_f32_e32 v2, v92, v2
	v_add_f32_e32 v2, v93, v2
	v_add_f32_e32 v2, v88, v2
	v_add_f32_e32 v2, v89, v2
	v_add_f32_e32 v2, v90, v2
	v_add_f32_e32 v2, v91, v2
	v_add_f32_e32 v2, v80, v2
	v_add_f32_e32 v2, v81, v2
	v_add_f32_e32 v2, v82, v2
	v_add_f32_e32 v2, v83, v2
	v_exp_f32_e32 v111, v144
	v_add_f32_e32 v2, v84, v2
	v_exp_f32_e32 v114, v145
	v_add_f32_e32 v2, v85, v2
	v_exp_f32_e32 v116, v142
	v_add_f32_e32 v2, v86, v2
	v_exp_f32_e32 v127, v143
	v_add_f32_e32 v2, v87, v2
	v_exp_f32_e32 v140, v140
	v_add_f32_e32 v2, v111, v2
	v_exp_f32_e32 v141, v141
	v_add_f32_e32 v2, v114, v2
	v_exp_f32_e32 v138, v138
	v_add_f32_e32 v2, v116, v2
	v_exp_f32_e32 v139, v139
	v_add_f32_e32 v2, v127, v2
	v_exp_f32_e32 v6, v136
	v_add_f32_e32 v2, v140, v2
	v_exp_f32_e32 v7, v137
	v_add_f32_e32 v2, v141, v2
	v_exp_f32_e32 v8, v134
	v_add_f32_e32 v2, v138, v2
	v_exp_f32_e32 v9, v135
	v_add_f32_e32 v2, v139, v2
	v_exp_f32_e32 v10, v132
	v_add_f32_e32 v2, v6, v2
	v_exp_f32_e32 v11, v133
	v_add_f32_e32 v2, v7, v2
	v_exp_f32_e32 v12, v130
	v_add_f32_e32 v2, v8, v2
	v_exp_f32_e32 v13, v131
	v_add_f32_e32 v2, v9, v2
	v_add_f32_e32 v2, v10, v2
	v_add_f32_e32 v2, v11, v2
	v_add_f32_e32 v2, v12, v2
	v_add_f32_e32 v112, v13, v2
	v_mov_b32_e32 v113, v112
	v_cvt_pk_bf16_f32 v2, v94, v95
	v_cvt_pk_bf16_f32 v3, v92, v93
	v_cvt_pk_bf16_f32 v4, v88, v89
	s_nop 1
	v_permlane32_swap_b32_e32 v112, v113
	v_cvt_pk_bf16_f32 v5, v90, v91
	v_permlane32_swap_b32_e32 v2, v4
	v_cvt_pk_bf16_f32 v88, v80, v81
	v_cvt_pk_bf16_f32 v89, v82, v83
	v_cvt_pk_bf16_f32 v90, v84, v85
	v_cvt_pk_bf16_f32 v91, v86, v87
	v_cvt_pk_bf16_f32 v92, v111, v114
	v_cvt_pk_bf16_f32 v93, v116, v127
	v_cvt_pk_bf16_f32 v94, v140, v141
	v_cvt_pk_bf16_f32 v95, v138, v139
	v_cvt_pk_bf16_f32 v130, v6, v7
	v_cvt_pk_bf16_f32 v131, v8, v9
	v_cvt_pk_bf16_f32 v132, v10, v11
	v_cvt_pk_bf16_f32 v133, v12, v13
	v_permlane32_swap_b32_e32 v3, v5
	v_permlane32_swap_b32_e32 v88, v90
	v_permlane32_swap_b32_e32 v89, v91
	v_permlane32_swap_b32_e32 v92, v94
	v_permlane32_swap_b32_e32 v93, v95
	v_permlane32_swap_b32_e32 v130, v132
	v_permlane32_swap_b32_e32 v131, v133
	s_mov_b32 s36, 0x50000
	v_add_co_u32_e32 v80, vcc, s36, v128
	s_nop 1
	v_addc_co_u32_e32 v81, vcc, 0, v129, vcc
	global_load_dwordx4 v[6:9], v[128:129], off offset:1024
	global_load_dwordx4 v[10:13], v[128:129], off
	global_load_dwordx4 v[84:87], v[80:81], off offset:1024
	s_nop 0
	global_load_dwordx4 v[80:83], v[80:81], off
	ds_read_b64_tr_b16 v[134:135], v151 offset:0
	ds_read_b64_tr_b16 v[136:137], v151 offset:0x800
	ds_read_b64_tr_b16 v[138:139], v151 offset:0x1000
	ds_read_b64_tr_b16 v[140:141], v151 offset:0x1800
	ds_read_b64_tr_b16 v[142:143], v151 offset:0x2000
	ds_read_b64_tr_b16 v[144:145], v151 offset:0x2800
	ds_read_b64_tr_b16 v[246:247], v151 offset:0x3000
	ds_read_b64_tr_b16 v[248:249], v151 offset:0x3800
	s_waitcnt lgkmcnt(6)
	s_nop 0
	v_mfma_f32_32x32x16_bf16 v[32:47], v[2:5], v[134:137], v[32:47]
	ds_read_b64_tr_b16 v[134:135], v151 offset:0x200
	ds_read_b64_tr_b16 v[136:137], v151 offset:0xa00
	s_waitcnt lgkmcnt(6)
	v_mfma_f32_32x32x16_bf16 v[32:47], v[88:91], v[138:141], v[32:47]
	ds_read_b64_tr_b16 v[138:139], v151 offset:0x1200
	ds_read_b64_tr_b16 v[140:141], v151 offset:0x1a00
	s_waitcnt lgkmcnt(6)
	v_mfma_f32_32x32x16_bf16 v[32:47], v[92:95], v[142:145], v[32:47]
	ds_read_b64_tr_b16 v[142:143], v151 offset:0x2200
	ds_read_b64_tr_b16 v[144:145], v151 offset:0x2a00
	s_waitcnt lgkmcnt(6)
	v_mfma_f32_32x32x16_bf16 v[32:47], v[130:133], v[246:249], v[32:47]
	ds_read_b64_tr_b16 v[246:247], v151 offset:0x3200
	ds_read_b64_tr_b16 v[248:249], v151 offset:0x3a00
	s_waitcnt lgkmcnt(6)
	v_mfma_f32_32x32x16_bf16 v[64:79], v[2:5], v[134:137], v[64:79]
	ds_read_b64_tr_b16 v[134:135], v151 offset:0x400
	ds_read_b64_tr_b16 v[136:137], v151 offset:0xc00
	s_waitcnt lgkmcnt(6)
	v_mfma_f32_32x32x16_bf16 v[64:79], v[88:91], v[138:141], v[64:79]
	ds_read_b64_tr_b16 v[138:139], v151 offset:0x1400
	ds_read_b64_tr_b16 v[140:141], v151 offset:0x1c00
	s_waitcnt lgkmcnt(6)
	v_mfma_f32_32x32x16_bf16 v[64:79], v[92:95], v[142:145], v[64:79]
	ds_read_b64_tr_b16 v[142:143], v151 offset:0x2400
	ds_read_b64_tr_b16 v[144:145], v151 offset:0x2c00
	s_waitcnt lgkmcnt(6)
	v_mfma_f32_32x32x16_bf16 v[64:79], v[130:133], v[246:249], v[64:79]
	ds_read_b64_tr_b16 v[246:247], v151 offset:0x3400
	ds_read_b64_tr_b16 v[248:249], v151 offset:0x3c00
	s_waitcnt lgkmcnt(6)
	v_mfma_f32_32x32x16_bf16 v[16:31], v[2:5], v[134:137], v[16:31]
	ds_read_b64_tr_b16 v[134:135], v151 offset:0x600
	ds_read_b64_tr_b16 v[136:137], v151 offset:0xe00
	s_waitcnt lgkmcnt(6)
	v_mfma_f32_32x32x16_bf16 v[16:31], v[88:91], v[138:141], v[16:31]
	ds_read_b64_tr_b16 v[138:139], v151 offset:0x1600
	ds_read_b64_tr_b16 v[140:141], v151 offset:0x1e00
	s_waitcnt lgkmcnt(6)
	v_mfma_f32_32x32x16_bf16 v[16:31], v[92:95], v[142:145], v[16:31]
	ds_read_b64_tr_b16 v[142:143], v151 offset:0x2600
	ds_read_b64_tr_b16 v[144:145], v151 offset:0x2e00
	s_waitcnt lgkmcnt(6)
	v_mfma_f32_32x32x16_bf16 v[16:31], v[130:133], v[246:249], v[16:31]
	ds_read_b64_tr_b16 v[246:247], v151 offset:0x3600
	ds_read_b64_tr_b16 v[248:249], v151 offset:0x3e00
	s_waitcnt lgkmcnt(6)
	v_mfma_f32_32x32x16_bf16 v[48:63], v[2:5], v[134:137], v[48:63]
	v_max_f32_e32 v2, v96, v96
	v_max_f32_e32 v3, v14, v14
	v_max_f32_e32 v2, v3, v2
	v_max3_f32 v2, v2, v243, v244
	v_max3_f32 v2, v2, v115, v245
	v_max3_f32 v2, v2, v117, v118
	v_max3_f32 v2, v2, v119, v120
	v_max3_f32 v2, v2, v121, v122
	v_max3_f32 v2, v2, v123, v124
	s_waitcnt lgkmcnt(4)
	v_mfma_f32_32x32x16_bf16 v[48:63], v[88:91], v[138:141], v[48:63]
	v_max3_f32 v2, v2, v125, v126
	v_max3_f32 v2, v2, v0, v15
	v_max3_f32 v2, v2, v97, v98
	v_max3_f32 v2, v2, v99, v100
	v_max3_f32 v2, v2, v101, v102
	v_max3_f32 v2, v2, v103, v104
	v_max3_f32 v2, v2, v105, v106
	v_max3_f32 v2, v2, v107, v108
	s_waitcnt lgkmcnt(2)
	v_mfma_f32_32x32x16_bf16 v[48:63], v[92:95], v[142:145], v[48:63]
	v_max3_f32 v2, v2, v109, v110
	v_mov_b32_e32 v3, v2
	s_nop 1
	v_permlane32_swap_b32_e32 v2, v3
	v_max_f32_e32 v3, v3, v3
	v_max_f32_e32 v2, v2, v2
	v_max_f32_e32 v2, v2, v3
	v_sub_f32_e32 v3, v2, v237
	s_mov_b32 s36, 0x42b504f3
	v_cmp_ge_f32_e32 vcc, s36, v3
	v_max_f32_e32 v3, v237, v237
	v_max_f32_e32 v2, v3, v2
	s_waitcnt lgkmcnt(0)
	v_mfma_f32_32x32x16_bf16 v[48:63], v[130:133], v[246:249], v[48:63]
	v_sub_f32_e32 v3, v237, v2
	v_mul_f32_e32 v3, 0x3e0293ee, v3
	v_exp_f32_e32 v3, v3
	s_cmp_eq_u64 vcc, exec
	s_cselect_b64 s[36:37], -1, 0
	s_waitcnt vmcnt(0)
	v_cndmask_b32_e64 v114, v3, 1.0, s[36:37]
	v_cmp_gt_f32_e32 vcc, 1.0, v114
	v_mov_b64_e32 v[168:169], v[6:7]
	v_mov_b64_e32 v[170:171], v[8:9]
	v_mov_b64_e32 v[194:195], v[84:85]
	v_mov_b64_e32 v[196:197], v[86:87]
	ds_write_b128 v156, v[10:13] offset:32768
	ds_write_b128 v157, v[80:83] offset:32768
	s_cbranch_vccz .LBB0_517
	s_mov_b64 s[48:49], exec
	v_readlane_b32 s52, v255, 58
	v_readlane_b32 s53, v255, 59
	s_and_b64 s[52:53], s[48:49], s[52:53]
	s_mov_b64 exec, s[52:53]
	ds_write_b32 v148, v114 offset:128
	s_or_b64 exec, exec, s[48:49]
	s_waitcnt lgkmcnt(0)
	ds_read_b128 v[4:7], v146 offset:128
	ds_read_b128 v[8:11], v146 offset:160
	ds_read_b128 v[80:83], v146 offset:192
	ds_read_b128 v[84:87], v146 offset:224
	s_waitcnt lgkmcnt(3)
	v_pk_mul_f32 v[64:65], v[4:5], v[64:65]
	v_pk_mul_f32 v[66:67], v[66:67], v[6:7]
	s_waitcnt lgkmcnt(2)
	v_pk_mul_f32 v[68:69], v[68:69], v[8:9]
	v_pk_mul_f32 v[70:71], v[70:71], v[10:11]
	s_waitcnt lgkmcnt(1)
	v_pk_mul_f32 v[72:73], v[72:73], v[80:81]
	v_pk_mul_f32 v[74:75], v[74:75], v[82:83]
	s_waitcnt lgkmcnt(0)
	v_pk_mul_f32 v[76:77], v[76:77], v[84:85]
	v_pk_mul_f32 v[46:47], v[46:47], v[86:87]
	v_pk_mul_f32 v[42:43], v[42:43], v[82:83]
	v_pk_mul_f32 v[38:39], v[38:39], v[10:11]
	v_pk_mul_f32 v[34:35], v[34:35], v[6:7]
	v_pk_mul_f32 v[44:45], v[44:45], v[84:85]
	v_pk_mul_f32 v[40:41], v[40:41], v[80:81]
	v_pk_mul_f32 v[36:37], v[36:37], v[8:9]
	v_pk_mul_f32 v[32:33], v[32:33], v[4:5]
	v_pk_mul_f32 v[78:79], v[78:79], v[86:87]
	v_pk_mul_f32 v[48:49], v[4:5], v[48:49]
	v_pk_mul_f32 v[50:51], v[50:51], v[6:7]
	v_pk_mul_f32 v[52:53], v[52:53], v[8:9]
	v_pk_mul_f32 v[54:55], v[54:55], v[10:11]
	v_pk_mul_f32 v[56:57], v[56:57], v[80:81]
	v_pk_mul_f32 v[58:59], v[58:59], v[82:83]
	v_pk_mul_f32 v[60:61], v[60:61], v[84:85]
	v_pk_mul_f32 v[30:31], v[30:31], v[86:87]
	v_pk_mul_f32 v[26:27], v[26:27], v[82:83]
	v_pk_mul_f32 v[22:23], v[22:23], v[10:11]
	v_pk_mul_f32 v[18:19], v[18:19], v[6:7]
	v_pk_mul_f32 v[28:29], v[28:29], v[84:85]
	v_pk_mul_f32 v[24:25], v[24:25], v[80:81]
	v_pk_mul_f32 v[20:21], v[20:21], v[8:9]
	v_pk_mul_f32 v[16:17], v[16:17], v[4:5]
	v_pk_mul_f32 v[62:63], v[62:63], v[86:87]

; #define SBAR() __builtin_amdgcn_sched_barrier(0)
; __device__ __forceinline__ void finishSM(f32x16& p0, f32x16& p1, float alpha, float& l_reg, bf16x8& pa0, bf16x8& pa1, bf16x8& pa2, bf16x8& pa3) {
; #pragma unroll
;   for (int r = 0; r < 16; ++r) p1[r] = __builtin_amdgcn_exp2f(p1[r]);
;   float ps = 0;
; #pragma unroll
;   for (int r = 0; r < 16; ++r) ps += p0[r];
; #pragma unroll
;   for (int r = 0; r < 16; ++r) ps += p1[r];
;   { auto rr = __builtin_amdgcn_permlane32_swap(__float_as_uint(ps), __float_as_uint(ps), false, false);
;     ps = __uint_as_float(rr[0]) + __uint_as_float(rr[1]); }
;   l_reg = l_reg * alpha + ps;
;     ...
;   PK4(p0, 0, pa0); PK4(p0, 8, pa1); PK4(p1, 0, pa2); PK4(p1, 8, pa3);
; template <int D0> __device__ __forceinline__ void pv_one(f32x16& od, int vb, bf16x8 pa0, bf16x8 pa1, bf16x8 pa2, bf16x8 pa3) {
;   const s16x4 l0 = tr_read<v_rd_off(D0, 0, 0)>(vb), h0 = tr_read<v_rd_off(D0, 0, 1)>(vb), l1 = tr_read<v_rd_off(D0, 1, 0)>(vb), h1 = tr_read<v_rd_off(D0, 1, 1)>(vb);
;   const s16x4 l2 = tr_read<v_rd_off(D0, 2, 0)>(vb), h2 = tr_read<v_rd_off(D0, 2, 1)>(vb), l3 = tr_read<v_rd_off(D0, 3, 0)>(vb), h3 = tr_read<v_rd_off(D0, 3, 1)>(vb);
;   asm volatile("s_waitcnt lgkmcnt(0)" ::: "memory"); SBAR();
;     ...
;   od = __builtin_amdgcn_mfma_f32_32x32x16_bf16(pa0, PK(l0, h0), od, 0, 0, 0);
;   od = __builtin_amdgcn_mfma_f32_32x32x16_bf16(pa1, PK(l1, h1), od, 0, 0, 0);
;   od = __builtin_amdgcn_mfma_f32_32x32x16_bf16(pa2, PK(l2, h2), od, 0, 0, 0);
;   od = __builtin_amdgcn_mfma_f32_32x32x16_bf16(pa3, PK(l3, h3), od, 0, 0, 0);
;     ...
; }
; __device__ __forceinline__ void pv_d0(f32x16* o, int vb, bf16x8 pa0, bf16x8 pa1, bf16x8 pa2, bf16x8 pa3) {
;   pv_one<0>(o[0], vb, pa0, pa1, pa2, pa3); pv_one<1>(o[1], vb, pa0, pa1, pa2, pa3); pv_one<2>(o[2], vb, pa0, pa1, pa2, pa3); pv_one<3>(o[3], vb, pa0, pa1, pa2, pa3);
.LBB0_581:
	s_or_b64 exec, exec, s[36:37]
	v_add_f32_e32 v110, 0, v121
	v_add_f32_e32 v110, v123, v110
	v_add_f32_e32 v110, v12, v110
	v_add_f32_e32 v110, v122, v110
	v_add_f32_e32 v110, v10, v110
	v_add_f32_e32 v110, v13, v110
	v_add_f32_e32 v110, v9, v110
	v_add_f32_e32 v110, v11, v110
	v_add_f32_e32 v110, v6, v110
	v_add_f32_e32 v110, v8, v110
	v_add_f32_e32 v110, v4, v110
	v_add_f32_e32 v110, v7, v110
	v_exp_f32_e32 v80, v124
	v_add_f32_e32 v110, v2, v110
	v_exp_f32_e32 v81, v125
	v_add_f32_e32 v110, v5, v110
	v_exp_f32_e32 v82, v126
	v_add_f32_e32 v110, v0, v110
	v_exp_f32_e32 v83, v130
	v_add_f32_e32 v110, v3, v110
	v_exp_f32_e32 v95, v131
	v_add_f32_e32 v110, v80, v110
	v_exp_f32_e32 v142, v132
	v_add_f32_e32 v110, v81, v110
	v_exp_f32_e32 v143, v133
	v_add_f32_e32 v110, v82, v110
	v_exp_f32_e32 v144, v134
	v_add_f32_e32 v110, v83, v110
	v_exp_f32_e32 v145, v135
	v_add_f32_e32 v110, v95, v110
	v_exp_f32_e32 v164, v136
	v_add_f32_e32 v110, v142, v110
	v_exp_f32_e32 v165, v137
	v_add_f32_e32 v110, v143, v110
	v_exp_f32_e32 v166, v138
	v_add_f32_e32 v110, v144, v110
	v_exp_f32_e32 v167, v139
	v_add_f32_e32 v110, v145, v110
	v_exp_f32_e32 v140, v140
	v_add_f32_e32 v110, v164, v110
	v_exp_f32_e32 v141, v141
	v_add_f32_e32 v110, v165, v110
	v_exp_f32_e32 v172, v127
	v_add_f32_e32 v110, v166, v110
	v_add_f32_e32 v110, v167, v110
	v_add_f32_e32 v110, v140, v110
	v_add_f32_e32 v110, v141, v110
	v_add_f32_e32 v110, v172, v110
	v_mov_b32_e32 v111, v110
	s_nop 1
	v_permlane32_swap_b32_e32 v110, v111
	v_cvt_pk_bf16_f32 v124, v121, v123
	v_cvt_pk_bf16_f32 v125, v12, v122
	v_cvt_pk_bf16_f32 v126, v10, v13
	v_cvt_pk_bf16_f32 v127, v9, v11
	v_cvt_pk_bf16_f32 v130, v6, v8
	v_cvt_pk_bf16_f32 v131, v4, v7
	v_cvt_pk_bf16_f32 v132, v2, v5
	v_cvt_pk_bf16_f32 v133, v0, v3
	v_cvt_pk_bf16_f32 v134, v80, v81
	v_cvt_pk_bf16_f32 v135, v82, v83
	v_cvt_pk_bf16_f32 v136, v95, v142
	v_cvt_pk_bf16_f32 v137, v143, v144
	v_cvt_pk_bf16_f32 v138, v145, v164
	v_cvt_pk_bf16_f32 v139, v165, v166
	v_cvt_pk_bf16_f32 v140, v167, v140
	v_cvt_pk_bf16_f32 v141, v141, v172
	s_nop 0
	v_permlane32_swap_b32_e32 v124, v126
	v_permlane32_swap_b32_e32 v125, v127
	v_permlane32_swap_b32_e32 v130, v132
	v_permlane32_swap_b32_e32 v131, v133
	v_permlane32_swap_b32_e32 v134, v136
	v_permlane32_swap_b32_e32 v135, v137
	v_permlane32_swap_b32_e32 v138, v140
	v_permlane32_swap_b32_e32 v139, v141
	s_mov_b32 s36, 0xa0000
	v_add_co_u32_e32 v6, vcc, s36, v128
	s_mov_b32 s36, 0xf0000
	s_nop 0
	v_addc_co_u32_e32 v7, vcc, 0, v129, vcc
	v_add_co_u32_e32 v10, vcc, s36, v128
	s_nop 1
	v_addc_co_u32_e32 v11, vcc, 0, v129, vcc
	global_load_dwordx4 v[2:5], v[6:7], off offset:1024
	s_nop 0
	global_load_dwordx4 v[6:9], v[6:7], off
	s_nop 0
	global_load_dwordx4 v[80:83], v[10:11], off offset:1024
	s_nop 0
	global_load_dwordx4 v[10:13], v[10:11], off
	ds_read_b64_tr_b16 v[142:143], v149 offset:0
	ds_read_b64_tr_b16 v[144:145], v149 offset:0x800
	ds_read_b64_tr_b16 v[164:165], v149 offset:0x1000
	ds_read_b64_tr_b16 v[166:167], v149 offset:0x1800
	ds_read_b64_tr_b16 v[244:245], v149 offset:0x2000
	ds_read_b64_tr_b16 v[246:247], v149 offset:0x2800
	ds_read_b64_tr_b16 v[172:173], v149 offset:0x3000
	ds_read_b64_tr_b16 v[174:175], v149 offset:0x3800
	s_waitcnt lgkmcnt(0)
	s_nop 0
	v_mfma_f32_32x32x16_bf16 v[32:47], v[124:127], v[142:145], v[32:47]
	ds_read_b64_tr_b16 v[142:143], v149 offset:0x200
	ds_read_b64_tr_b16 v[144:145], v149 offset:0xa00
	v_mfma_f32_32x32x16_bf16 v[32:47], v[130:133], v[164:167], v[32:47]
	ds_read_b64_tr_b16 v[164:165], v149 offset:0x1200
	ds_read_b64_tr_b16 v[166:167], v149 offset:0x1a00
	v_mfma_f32_32x32x16_bf16 v[32:47], v[134:137], v[244:247], v[32:47]
	v_mfma_f32_32x32x16_bf16 v[32:47], v[138:141], v[172:175], v[32:47]
	ds_read_b64_tr_b16 v[172:173], v149 offset:0x2200
	ds_read_b64_tr_b16 v[174:175], v149 offset:0x2a00
	ds_read_b64_tr_b16 v[244:245], v149 offset:0x3200
	ds_read_b64_tr_b16 v[246:247], v149 offset:0x3a00
	s_waitcnt lgkmcnt(6)
	v_mfma_f32_32x32x16_bf16 v[64:79], v[124:127], v[142:145], v[64:79]
	ds_read_b64_tr_b16 v[142:143], v149 offset:0x400
	ds_read_b64_tr_b16 v[144:145], v149 offset:0xc00
	s_waitcnt lgkmcnt(6)
	v_mfma_f32_32x32x16_bf16 v[64:79], v[130:133], v[164:167], v[64:79]
	ds_read_b64_tr_b16 v[164:165], v149 offset:0x1400
	ds_read_b64_tr_b16 v[166:167], v149 offset:0x1c00
	s_waitcnt lgkmcnt(6)
	v_mfma_f32_32x32x16_bf16 v[64:79], v[134:137], v[172:175], v[64:79]
	ds_read_b64_tr_b16 v[172:173], v149 offset:0x2400
	ds_read_b64_tr_b16 v[174:175], v149 offset:0x2c00
	s_waitcnt lgkmcnt(6)
; #define SBAR() __builtin_amdgcn_sched_barrier(0)
; template <int D0> __device__ __forceinline__ void pv_one(f32x16& od, int vb, bf16x8 pa0, bf16x8 pa1, bf16x8 pa2, bf16x8 pa3) {
;   const s16x4 l0 = tr_read<v_rd_off(D0, 0, 0)>(vb), h0 = tr_read<v_rd_off(D0, 0, 1)>(vb), l1 = tr_read<v_rd_off(D0, 1, 0)>(vb), h1 = tr_read<v_rd_off(D0, 1, 1)>(vb);
;   const s16x4 l2 = tr_read<v_rd_off(D0, 2, 0)>(vb), h2 = tr_read<v_rd_off(D0, 2, 1)>(vb), l3 = tr_read<v_rd_off(D0, 3, 0)>(vb), h3 = tr_read<v_rd_off(D0, 3, 1)>(vb);
;   asm volatile("s_waitcnt lgkmcnt(0)" ::: "memory"); SBAR();
;     ...
;   od = __builtin_amdgcn_mfma_f32_32x32x16_bf16(pa0, PK(l0, h0), od, 0, 0, 0);
;   od = __builtin_amdgcn_mfma_f32_32x32x16_bf16(pa1, PK(l1, h1), od, 0, 0, 0);
;   od = __builtin_amdgcn_mfma_f32_32x32x16_bf16(pa2, PK(l2, h2), od, 0, 0, 0);
;   od = __builtin_amdgcn_mfma_f32_32x32x16_bf16(pa3, PK(l3, h3), od, 0, 0, 0);
;     ...
; }
; __device__ __forceinline__ void pv_d0(f32x16* o, int vb, bf16x8 pa0, bf16x8 pa1, bf16x8 pa2, bf16x8 pa3) {
;   pv_one<0>(o[0], vb, pa0, pa1, pa2, pa3); pv_one<1>(o[1], vb, pa0, pa1, pa2, pa3); pv_one<2>(o[2], vb, pa0, pa1, pa2, pa3); pv_one<3>(o[3], vb, pa0, pa1, pa2, pa3);
	v_mfma_f32_32x32x16_bf16 v[64:79], v[138:141], v[244:247], v[64:79]
	ds_read_b64_tr_b16 v[244:245], v149 offset:0x3400
	ds_read_b64_tr_b16 v[246:247], v149 offset:0x3c00
	s_waitcnt lgkmcnt(6)
	v_mfma_f32_32x32x16_bf16 v[16:31], v[124:127], v[142:145], v[16:31]
	ds_read_b64_tr_b16 v[142:143], v149 offset:0x600
	ds_read_b64_tr_b16 v[144:145], v149 offset:0xe00
	s_waitcnt lgkmcnt(6)
	v_mfma_f32_32x32x16_bf16 v[16:31], v[130:133], v[164:167], v[16:31]
	ds_read_b64_tr_b16 v[164:165], v149 offset:0x1600
	ds_read_b64_tr_b16 v[166:167], v149 offset:0x1e00
	s_waitcnt lgkmcnt(6)
	v_mfma_f32_32x32x16_bf16 v[16:31], v[134:137], v[172:175], v[16:31]
	ds_read_b64_tr_b16 v[172:173], v149 offset:0x2600
	ds_read_b64_tr_b16 v[174:175], v149 offset:0x2e00
	s_waitcnt lgkmcnt(6)
	v_mfma_f32_32x32x16_bf16 v[16:31], v[138:141], v[244:247], v[16:31]
	ds_read_b64_tr_b16 v[244:245], v149 offset:0x3600
	ds_read_b64_tr_b16 v[246:247], v149 offset:0x3e00
	s_waitcnt lgkmcnt(6)
	v_mfma_f32_32x32x16_bf16 v[48:63], v[124:127], v[142:145], v[48:63]
	v_max_f32_e32 v0, v117, v117
	v_max_f32_e32 v95, v115, v115
	v_max_f32_e32 v0, v95, v0
	v_max3_f32 v0, v0, v118, v119
	v_max3_f32 v0, v0, v120, v100
	v_max3_f32 v0, v0, v101, v102
	v_max3_f32 v0, v0, v103, v104
	v_max3_f32 v0, v0, v105, v106
	v_max3_f32 v0, v0, v107, v108
	s_waitcnt lgkmcnt(4)
	v_mfma_f32_32x32x16_bf16 v[48:63], v[130:133], v[164:167], v[48:63]
	v_max3_f32 v0, v0, v109, v94
	v_max3_f32 v0, v0, v14, v15
	v_max3_f32 v0, v0, v96, v97
	v_max3_f32 v0, v0, v98, v99
	v_max3_f32 v0, v0, v84, v85
	v_max3_f32 v0, v0, v86, v87
	v_max3_f32 v0, v0, v88, v89
	v_max3_f32 v0, v0, v90, v91
	s_waitcnt lgkmcnt(2)
	v_mfma_f32_32x32x16_bf16 v[48:63], v[134:137], v[172:175], v[48:63]
	v_max3_f32 v0, v0, v92, v93
	v_mov_b32_e32 v95, v0
	s_nop 1
	v_permlane32_swap_b32_e32 v0, v95
	v_max_f32_e32 v95, v95, v95
	v_max_f32_e32 v0, v0, v0
	v_max_f32_e32 v0, v0, v95
	v_sub_f32_e32 v95, v0, v116
	s_mov_b32 s36, 0x42b504f3
	v_cmp_ge_f32_e32 vcc, s36, v95
	v_max_f32_e32 v95, v116, v116
	v_max_f32_e32 v95, v95, v0
	s_waitcnt lgkmcnt(0)
	v_mfma_f32_32x32x16_bf16 v[48:63], v[138:141], v[244:247], v[48:63]
	v_sub_f32_e32 v0, v116, v95
	v_mul_f32_e32 v0, 0x3e0293ee, v0
	v_exp_f32_e32 v0, v0
	s_cmp_eq_u64 vcc, exec
	s_cselect_b64 s[36:37], -1, 0
	s_waitcnt vmcnt(0)
	v_cndmask_b32_e64 v0, v0, 1.0, s[36:37]
	v_cmp_gt_f32_e32 vcc, 1.0, v0
	v_mov_b64_e32 v[168:169], v[2:3]
	v_mov_b64_e32 v[170:171], v[4:5]
	v_mov_b64_e32 v[194:195], v[80:81]
	v_mov_b64_e32 v[196:197], v[82:83]
	ds_write_b128 v156, v[6:9] offset:49152
	ds_write_b128 v157, v[10:13] offset:49152
	s_cbranch_vccz .LBB0_585
	s_mov_b64 s[48:49], exec
	v_readlane_b32 s50, v255, 58
	v_readlane_b32 s51, v255, 59
	s_and_b64 s[50:51], s[48:49], s[50:51]
	s_mov_b64 exec, s[50:51]
	ds_write_b32 v148, v0 offset:128
	s_or_b64 exec, exec, s[48:49]
	s_waitcnt lgkmcnt(0)
	ds_read_b128 v[2:5], v146 offset:128
	ds_read_b128 v[6:9], v146 offset:160
	ds_read_b128 v[10:13], v146 offset:192
	ds_read_b128 v[80:83], v146 offset:224
	s_waitcnt lgkmcnt(3)
	v_pk_mul_f32 v[64:65], v[2:3], v[64:65]
	v_pk_mul_f32 v[66:67], v[66:67], v[4:5]
	s_waitcnt lgkmcnt(2)
	v_pk_mul_f32 v[68:69], v[68:69], v[6:7]
	v_pk_mul_f32 v[70:71], v[70:71], v[8:9]
	s_waitcnt lgkmcnt(1)
	v_pk_mul_f32 v[72:73], v[72:73], v[10:11]
	v_pk_mul_f32 v[74:75], v[74:75], v[12:13]
	s_waitcnt lgkmcnt(0)
	v_pk_mul_f32 v[76:77], v[76:77], v[80:81]
	v_pk_mul_f32 v[46:47], v[46:47], v[82:83]
	v_pk_mul_f32 v[42:43], v[42:43], v[12:13]
	v_pk_mul_f32 v[38:39], v[38:39], v[8:9]
	v_pk_mul_f32 v[34:35], v[34:35], v[4:5]
	v_pk_mul_f32 v[44:45], v[44:45], v[80:81]
	v_pk_mul_f32 v[40:41], v[40:41], v[10:11]
	v_pk_mul_f32 v[36:37], v[36:37], v[6:7]
	v_pk_mul_f32 v[32:33], v[32:33], v[2:3]
	v_pk_mul_f32 v[78:79], v[78:79], v[82:83]
	v_pk_mul_f32 v[48:49], v[2:3], v[48:49]
	v_pk_mul_f32 v[50:51], v[50:51], v[4:5]
	v_pk_mul_f32 v[52:53], v[52:53], v[6:7]
	v_pk_mul_f32 v[54:55], v[54:55], v[8:9]
	v_pk_mul_f32 v[56:57], v[56:57], v[10:11]
	v_pk_mul_f32 v[58:59], v[58:59], v[12:13]
	v_pk_mul_f32 v[60:61], v[60:61], v[80:81]
	v_pk_mul_f32 v[30:31], v[30:31], v[82:83]
	v_pk_mul_f32 v[26:27], v[26:27], v[12:13]
	v_pk_mul_f32 v[22:23], v[22:23], v[8:9]
	v_pk_mul_f32 v[18:19], v[18:19], v[4:5]
	v_pk_mul_f32 v[28:29], v[28:29], v[80:81]
	v_pk_mul_f32 v[24:25], v[24:25], v[10:11]
	v_pk_mul_f32 v[20:21], v[20:21], v[6:7]
	v_pk_mul_f32 v[16:17], v[16:17], v[2:3]
	v_pk_mul_f32 v[62:63], v[62:63], v[82:83]

; __device__ __forceinline__ void finishSM(f32x16& p0, f32x16& p1, float alpha, float& l_reg, bf16x8& pa0, bf16x8& pa1, bf16x8& pa2, bf16x8& pa3) {
; #pragma unroll
;   for (int r = 0; r < 16; ++r) p1[r] = __builtin_amdgcn_exp2f(p1[r]);
;   float ps = 0;
; #pragma unroll
;   for (int r = 0; r < 16; ++r) ps += p0[r];
; #pragma unroll
;   for (int r = 0; r < 16; ++r) ps += p1[r];
;   { auto rr = __builtin_amdgcn_permlane32_swap(__float_as_uint(ps), __float_as_uint(ps), false, false);
;     ps = __uint_as_float(rr[0]) + __uint_as_float(rr[1]); }
;   l_reg = l_reg * alpha + ps;
;     ...
;   PK4(p0, 0, pa0); PK4(p0, 8, pa1); PK4(p1, 0, pa2); PK4(p1, 8, pa3);
; template <int DK, bool QL>
; __device__ __forceinline__ void qkt(f32x16& p0, f32x16& p1, const bf16* Ks, const bf16x8* qr, const char* ql, int r32, int hi) {
;   p0 = f32x16{}; p1 = f32x16{};
; #pragma unroll
;   for (int d0 = 0; d0 < DK / 16; ++d0) { int cb = (d0 * 16 + hi * 8) * 2;
;     const bf16x8 qv = QL ? *reinterpret_cast<const bf16x8*>(ql + d0 * 1024) : qr[d0];
;     bf16x8 b0 = *reinterpret_cast<const bf16x8*>((const char*)Ks + kswz<DK>(r32, cb));
;     bf16x8 b1 = *reinterpret_cast<const bf16x8*>((const char*)Ks + kswz<DK>(32 + r32, cb));
;     p0 = __builtin_amdgcn_mfma_f32_32x32x16_bf16(b0, qv, p0, 0, 0, 0);
;     p1 = __builtin_amdgcn_mfma_f32_32x32x16_bf16(b1, qv, p1, 0, 0, 0); }
.LBB0_660:
	ds_read_b128 v[66:69], v153
	ds_read_b128 v[70:73], v159 offset:49152
	ds_read_b128 v[74:77], v159 offset:57344
	ds_read_b128 v[218:221], v153 offset:1024
	ds_read_b128 v[222:225], v207 offset:49152
	ds_read_b128 v[226:229], v207 offset:57344
	v_add_f32_e32 v130, 0, v145
	v_add_f32_e32 v130, v216, v130
	s_waitcnt lgkmcnt(4)
	v_mfma_f32_32x32x16_bf16 v[82:97], v[70:73], v[66:69], 0
	v_add_f32_e32 v130, v131, v130
	v_add_f32_e32 v130, v215, v130
	v_add_f32_e32 v130, v132, v130
	v_add_f32_e32 v130, v144, v130
	v_add_f32_e32 v130, v133, v130
	v_add_f32_e32 v130, v143, v130
	v_add_f32_e32 v130, v140, v130
	s_waitcnt lgkmcnt(3)
	v_mfma_f32_32x32x16_bf16 v[66:81], v[74:77], v[66:69], 0
	v_add_f32_e32 v130, v142, v130
	v_add_f32_e32 v130, v139, v130
	v_add_f32_e32 v130, v141, v130
	v_exp_f32_e32 v126, v126
	v_add_f32_e32 v130, v136, v130
	v_exp_f32_e32 v127, v127
	v_add_f32_e32 v130, v138, v130
	s_waitcnt lgkmcnt(1)
	v_mfma_f32_32x32x16_bf16 v[82:97], v[222:225], v[218:221], v[82:97]
	v_exp_f32_e32 v124, v124
	v_add_f32_e32 v130, v135, v130
	v_exp_f32_e32 v125, v125
	v_add_f32_e32 v130, v137, v130
	v_exp_f32_e32 v118, v118
	v_add_f32_e32 v130, v126, v130
	v_exp_f32_e32 v119, v119
	s_waitcnt lgkmcnt(0)
	v_mfma_f32_32x32x16_bf16 v[66:81], v[226:229], v[218:221], v[66:81]
	ds_read_b128 v[218:221], v153 offset:2048
	ds_read_b128 v[222:225], v161 offset:49152
	ds_read_b128 v[226:229], v161 offset:57344
	v_add_f32_e32 v130, v127, v130
	v_exp_f32_e32 v116, v116
	v_add_f32_e32 v130, v124, v130
	v_exp_f32_e32 v117, v117
	v_add_f32_e32 v130, v125, v130
	v_exp_f32_e32 v114, v114
	s_waitcnt lgkmcnt(1)
	v_mfma_f32_32x32x16_bf16 v[82:97], v[222:225], v[218:221], v[82:97]
	v_add_f32_e32 v130, v118, v130
	v_exp_f32_e32 v115, v115
	v_add_f32_e32 v130, v119, v130
	v_exp_f32_e32 v128, v128
	v_add_f32_e32 v130, v116, v130
	v_exp_f32_e32 v129, v129
	v_add_f32_e32 v130, v117, v130
	s_waitcnt lgkmcnt(0)
	v_mfma_f32_32x32x16_bf16 v[66:81], v[226:229], v[218:221], v[66:81]
	ds_read_b128 v[218:221], v153 offset:3072
	ds_read_b128 v[222:225], v160 offset:49152
	ds_read_b128 v[226:229], v160 offset:57344
	v_exp_f32_e32 v122, v122
	v_add_f32_e32 v130, v114, v130
	v_exp_f32_e32 v123, v123
	v_add_f32_e32 v130, v115, v130
	v_exp_f32_e32 v120, v120
	v_add_f32_e32 v130, v128, v130
	s_waitcnt lgkmcnt(1)
	v_mfma_f32_32x32x16_bf16 v[82:97], v[222:225], v[218:221], v[82:97]
	v_exp_f32_e32 v121, v121
	v_add_f32_e32 v130, v129, v130
	v_add_f32_e32 v130, v122, v130
	v_add_f32_e32 v130, v123, v130
	v_add_f32_e32 v130, v120, v130
	v_add_f32_e32 v212, v121, v130
	v_mov_b32_e32 v213, v212
	s_waitcnt lgkmcnt(0)
	v_mfma_f32_32x32x16_bf16 v[66:81], v[226:229], v[218:221], v[66:81]
	ds_read_b128 v[218:221], v153 offset:4096
	ds_read_b128 v[222:225], v158 offset:49152
	ds_read_b128 v[226:229], v158 offset:57344
	v_permlane32_swap_b32_e32 v212, v213
	s_waitcnt lgkmcnt(1)
	v_mfma_f32_32x32x16_bf16 v[82:97], v[222:225], v[218:221], v[82:97]
	s_waitcnt lgkmcnt(0)
	v_mfma_f32_32x32x16_bf16 v[66:81], v[226:229], v[218:221], v[66:81]
	ds_read_b128 v[218:221], v153 offset:5120
	ds_read_b128 v[222:225], v156 offset:49152
	ds_read_b128 v[226:229], v156 offset:57344
	s_waitcnt lgkmcnt(1)
	v_mfma_f32_32x32x16_bf16 v[82:97], v[222:225], v[218:221], v[82:97]
	s_waitcnt lgkmcnt(0)
	v_mfma_f32_32x32x16_bf16 v[66:81], v[226:229], v[218:221], v[66:81]
	ds_read_b128 v[218:221], v153 offset:6144
	ds_read_b128 v[222:225], v157 offset:49152
	ds_read_b128 v[226:229], v157 offset:57344
	s_waitcnt lgkmcnt(1)
	v_mfma_f32_32x32x16_bf16 v[82:97], v[222:225], v[218:221], v[82:97]
	s_waitcnt lgkmcnt(0)
	v_mfma_f32_32x32x16_bf16 v[66:81], v[226:229], v[218:221], v[66:81]
	ds_read_b128 v[218:221], v153 offset:7168
	ds_read_b128 v[222:225], v176 offset:49152
	ds_read_b128 v[226:229], v176 offset:57344
	v_cvt_pk_bf16_f32 v130, v145, v216
	v_cvt_pk_bf16_f32 v131, v131, v215
	v_cvt_pk_bf16_f32 v132, v132, v144
	v_cvt_pk_bf16_f32 v133, v133, v143
	v_cvt_pk_bf16_f32 v140, v140, v142
	v_cvt_pk_bf16_f32 v141, v139, v141
	s_waitcnt lgkmcnt(1)
	v_mfma_f32_32x32x16_bf16 v[82:97], v[222:225], v[218:221], v[82:97]
	v_cvt_pk_bf16_f32 v142, v136, v138
	v_cvt_pk_bf16_f32 v143, v135, v137
	v_cvt_pk_bf16_f32 v136, v126, v127
	v_cvt_pk_bf16_f32 v137, v124, v125
	v_cvt_pk_bf16_f32 v138, v118, v119
	v_cvt_pk_bf16_f32 v139, v116, v117
	v_cvt_pk_bf16_f32 v214, v114, v115
	s_waitcnt lgkmcnt(0)
	v_mfma_f32_32x32x16_bf16 v[66:81], v[226:229], v[218:221], v[66:81]
	v_cvt_pk_bf16_f32 v215, v128, v129
	v_cvt_pk_bf16_f32 v216, v122, v123
	v_permlane32_swap_b32_e32 v130, v132
	v_cvt_pk_bf16_f32 v217, v120, v121
	v_permlane32_swap_b32_e32 v214, v216
	v_permlane32_swap_b32_e32 v131, v133
	v_permlane32_swap_b32_e32 v140, v142
	v_permlane32_swap_b32_e32 v141, v143
	v_permlane32_swap_b32_e32 v136, v138
	v_permlane32_swap_b32_e32 v137, v139
	v_permlane32_swap_b32_e32 v215, v217
	s_mov_b32 s2, 0xfff10000
	v_add_co_u32_e32 v118, vcc, s2, v146
	s_mov_b32 s2, 0xfff60000
	s_nop 0
	v_addc_co_u32_e32 v119, vcc, -1, v147, vcc
	v_add_co_u32_e32 v122, vcc, s2, v146
	s_nop 1
	v_addc_co_u32_e32 v123, vcc, -1, v147, vcc
	global_load_dwordx4 v[114:117], v[118:119], off
	s_nop 0
	global_load_dwordx4 v[118:121], v[118:119], off offset:-512
	s_nop 0
	global_load_dwordx4 v[126:129], v[122:123], off
	s_nop 0
	global_load_dwordx4 v[122:125], v[122:123], off offset:-512
	ds_read_b64_tr_b16 v[218:219], v152 offset:0
	ds_read_b64_tr_b16 v[220:221], v152 offset:0x800
	ds_read_b64_tr_b16 v[222:223], v152 offset:0x1000
	ds_read_b64_tr_b16 v[224:225], v152 offset:0x1800
	ds_read_b64_tr_b16 v[226:227], v152 offset:0x2000
	ds_read_b64_tr_b16 v[228:229], v152 offset:0x2800
	ds_read_b64_tr_b16 v[230:231], v152 offset:0x3000
	ds_read_b64_tr_b16 v[232:233], v152 offset:0x3800
	s_waitcnt lgkmcnt(6)
; #define SBAR() __builtin_amdgcn_sched_barrier(0)
; template <int D0> __device__ __forceinline__ void pv_one(f32x16& od, int vb, bf16x8 pa0, bf16x8 pa1, bf16x8 pa2, bf16x8 pa3) {
;   const s16x4 l0 = tr_read<v_rd_off(D0, 0, 0)>(vb), h0 = tr_read<v_rd_off(D0, 0, 1)>(vb), l1 = tr_read<v_rd_off(D0, 1, 0)>(vb), h1 = tr_read<v_rd_off(D0, 1, 1)>(vb);
;   const s16x4 l2 = tr_read<v_rd_off(D0, 2, 0)>(vb), h2 = tr_read<v_rd_off(D0, 2, 1)>(vb), l3 = tr_read<v_rd_off(D0, 3, 0)>(vb), h3 = tr_read<v_rd_off(D0, 3, 1)>(vb);
;   asm volatile("s_waitcnt lgkmcnt(0)" ::: "memory"); SBAR();
;     ...
;   od = __builtin_amdgcn_mfma_f32_32x32x16_bf16(pa0, PK(l0, h0), od, 0, 0, 0);
;   od = __builtin_amdgcn_mfma_f32_32x32x16_bf16(pa1, PK(l1, h1), od, 0, 0, 0);
;   od = __builtin_amdgcn_mfma_f32_32x32x16_bf16(pa2, PK(l2, h2), od, 0, 0, 0);
;   od = __builtin_amdgcn_mfma_f32_32x32x16_bf16(pa3, PK(l3, h3), od, 0, 0, 0);
;     ...
; }
; __device__ __forceinline__ void pv_d0(f32x16* o, int vb, bf16x8 pa0, bf16x8 pa1, bf16x8 pa2, bf16x8 pa3) {
;   pv_one<0>(o[0], vb, pa0, pa1, pa2, pa3); pv_one<1>(o[1], vb, pa0, pa1, pa2, pa3); pv_one<2>(o[2], vb, pa0, pa1, pa2, pa3); pv_one<3>(o[3], vb, pa0, pa1, pa2, pa3);
	s_nop 0
	v_mfma_f32_32x32x16_bf16 v[18:33], v[130:133], v[218:221], v[18:33]
	ds_read_b64_tr_b16 v[218:219], v152 offset:0x200
	ds_read_b64_tr_b16 v[220:221], v152 offset:0xa00
	s_waitcnt lgkmcnt(6)
	v_mfma_f32_32x32x16_bf16 v[18:33], v[140:143], v[222:225], v[18:33]
	ds_read_b64_tr_b16 v[222:223], v152 offset:0x1200
	ds_read_b64_tr_b16 v[224:225], v152 offset:0x1a00
	s_waitcnt lgkmcnt(6)
	v_mfma_f32_32x32x16_bf16 v[18:33], v[136:139], v[226:229], v[18:33]
	ds_read_b64_tr_b16 v[226:227], v152 offset:0x2200
	ds_read_b64_tr_b16 v[228:229], v152 offset:0x2a00
	s_waitcnt lgkmcnt(6)
	v_mfma_f32_32x32x16_bf16 v[18:33], v[214:217], v[230:233], v[18:33]
	ds_read_b64_tr_b16 v[230:231], v152 offset:0x3200
	ds_read_b64_tr_b16 v[232:233], v152 offset:0x3a00
	s_waitcnt lgkmcnt(6)
	v_mfma_f32_32x32x16_bf16 v[50:65], v[130:133], v[218:221], v[50:65]
	ds_read_b64_tr_b16 v[218:219], v152 offset:0x400
	ds_read_b64_tr_b16 v[220:221], v152 offset:0xc00
	s_waitcnt lgkmcnt(6)
	v_mfma_f32_32x32x16_bf16 v[50:65], v[140:143], v[222:225], v[50:65]
	ds_read_b64_tr_b16 v[222:223], v152 offset:0x1400
	ds_read_b64_tr_b16 v[224:225], v152 offset:0x1c00
	s_waitcnt lgkmcnt(6)
	v_mfma_f32_32x32x16_bf16 v[50:65], v[136:139], v[226:229], v[50:65]
	ds_read_b64_tr_b16 v[226:227], v152 offset:0x2400
	ds_read_b64_tr_b16 v[228:229], v152 offset:0x2c00
	s_waitcnt lgkmcnt(6)
	v_mfma_f32_32x32x16_bf16 v[50:65], v[214:217], v[230:233], v[50:65]
	ds_read_b64_tr_b16 v[230:231], v152 offset:0x3400
	ds_read_b64_tr_b16 v[232:233], v152 offset:0x3c00
	s_waitcnt lgkmcnt(6)
	v_mfma_f32_32x32x16_bf16 v[2:17], v[130:133], v[218:221], v[2:17]
	ds_read_b64_tr_b16 v[218:219], v152 offset:0x600
	ds_read_b64_tr_b16 v[220:221], v152 offset:0xe00
	s_waitcnt lgkmcnt(6)
	v_mfma_f32_32x32x16_bf16 v[2:17], v[140:143], v[222:225], v[2:17]
	ds_read_b64_tr_b16 v[222:223], v152 offset:0x1600
	ds_read_b64_tr_b16 v[224:225], v152 offset:0x1e00
	s_waitcnt lgkmcnt(6)
	v_mfma_f32_32x32x16_bf16 v[2:17], v[136:139], v[226:229], v[2:17]
	ds_read_b64_tr_b16 v[226:227], v152 offset:0x2600
	ds_read_b64_tr_b16 v[228:229], v152 offset:0x2e00
	s_waitcnt lgkmcnt(6)
	v_mfma_f32_32x32x16_bf16 v[2:17], v[214:217], v[230:233], v[2:17]
	ds_read_b64_tr_b16 v[230:231], v152 offset:0x3600
	ds_read_b64_tr_b16 v[232:233], v152 offset:0x3e00
	s_waitcnt lgkmcnt(6)
	v_mfma_f32_32x32x16_bf16 v[34:49], v[130:133], v[218:221], v[34:49]
	v_max_f32_e32 v130, v83, v83
	v_max_f32_e32 v131, v82, v82
	v_max_f32_e32 v130, v131, v130
	v_max3_f32 v130, v130, v84, v85
	v_max3_f32 v130, v130, v86, v87
	v_max3_f32 v130, v130, v88, v89
	v_max3_f32 v130, v130, v90, v91
	v_max3_f32 v130, v130, v92, v93
	v_max3_f32 v130, v130, v94, v95
	s_waitcnt lgkmcnt(4)
	v_mfma_f32_32x32x16_bf16 v[34:49], v[140:143], v[222:225], v[34:49]
	v_max3_f32 v130, v130, v96, v97
	v_max3_f32 v130, v130, v66, v67
	v_max3_f32 v130, v130, v68, v69
	v_max3_f32 v130, v130, v70, v71
	v_max3_f32 v130, v130, v72, v73
	v_max3_f32 v130, v130, v74, v75
	v_max3_f32 v130, v130, v76, v77
	v_max3_f32 v130, v130, v78, v79
	s_waitcnt lgkmcnt(2)
	v_mfma_f32_32x32x16_bf16 v[34:49], v[136:139], v[226:229], v[34:49]
	v_max3_f32 v130, v130, v80, v81
	v_mov_b32_e32 v131, v130
	s_nop 1
	v_permlane32_swap_b32_e32 v130, v131
	v_max_f32_e32 v131, v131, v131
	v_max_f32_e32 v130, v130, v130
	v_max_f32_e32 v130, v130, v131
	v_sub_f32_e32 v131, v130, v134
	s_mov_b32 s2, 0x42b504f3
	v_cmp_ge_f32_e32 vcc, s2, v131
	v_max_f32_e32 v131, v134, v134
	v_max_f32_e32 v130, v131, v130
	s_waitcnt lgkmcnt(0)
	v_mfma_f32_32x32x16_bf16 v[34:49], v[214:217], v[230:233], v[34:49]
	v_sub_f32_e32 v131, v134, v130
	v_mul_f32_e32 v131, 0x3e0293ee, v131
	v_exp_f32_e32 v131, v131
	s_cmp_eq_u64 vcc, exec
	s_cselect_b64 s[2:3], -1, 0
	s_waitcnt vmcnt(4)
	v_cndmask_b32_e64 v214, v131, 1.0, s[2:3]
	v_cmp_gt_f32_e32 vcc, 1.0, v214
	s_waitcnt vmcnt(4)
	ds_write_b128 v177, v[98:101] offset:32768
	ds_write_b128 v208, v[102:105] offset:32768
	s_cbranch_vccz .LBB0_664
	s_and_saveexec_b64 s[4:5], s[0:1]
	ds_write_b32 v149, v214 offset:128
	s_or_b64 exec, exec, s[4:5]
	s_waitcnt lgkmcnt(0)
	v_add_u32_e32 v131, v148, v0
	ds_read_b128 v[136:139], v131 offset:128
	ds_read_b128 v[140:143], v131 offset:160
	ds_read_b128 v[216:219], v131 offset:192
	ds_read_b128 v[220:223], v131 offset:224
	s_waitcnt lgkmcnt(3)
	v_pk_mul_f32 v[50:51], v[136:137], v[50:51]
	v_pk_mul_f32 v[52:53], v[52:53], v[138:139]
	s_waitcnt lgkmcnt(2)
	v_pk_mul_f32 v[54:55], v[54:55], v[140:141]
	v_pk_mul_f32 v[56:57], v[56:57], v[142:143]
	s_waitcnt lgkmcnt(1)
	v_pk_mul_f32 v[58:59], v[58:59], v[216:217]
	v_pk_mul_f32 v[60:61], v[60:61], v[218:219]
	s_waitcnt lgkmcnt(0)
	v_pk_mul_f32 v[62:63], v[62:63], v[220:221]
	v_pk_mul_f32 v[30:31], v[30:31], v[220:221]
	v_pk_mul_f32 v[26:27], v[26:27], v[216:217]
	v_pk_mul_f32 v[22:23], v[22:23], v[140:141]
	v_pk_mul_f32 v[32:33], v[32:33], v[222:223]
	v_pk_mul_f32 v[28:29], v[28:29], v[218:219]
	v_pk_mul_f32 v[24:25], v[24:25], v[142:143]
	v_pk_mul_f32 v[20:21], v[20:21], v[138:139]
	v_pk_mul_f32 v[18:19], v[18:19], v[136:137]
	v_pk_mul_f32 v[64:65], v[64:65], v[222:223]
	v_pk_mul_f32 v[34:35], v[136:137], v[34:35]
	v_pk_mul_f32 v[36:37], v[36:37], v[138:139]
	v_pk_mul_f32 v[38:39], v[38:39], v[140:141]
	v_pk_mul_f32 v[40:41], v[40:41], v[142:143]
	v_pk_mul_f32 v[42:43], v[42:43], v[216:217]
	v_pk_mul_f32 v[44:45], v[44:45], v[218:219]
	v_pk_mul_f32 v[46:47], v[46:47], v[220:221]
	v_pk_mul_f32 v[14:15], v[14:15], v[220:221]
	v_pk_mul_f32 v[10:11], v[10:11], v[216:217]
	v_pk_mul_f32 v[6:7], v[6:7], v[140:141]
	v_pk_mul_f32 v[16:17], v[16:17], v[222:223]
	v_pk_mul_f32 v[12:13], v[12:13], v[218:219]
	v_pk_mul_f32 v[8:9], v[8:9], v[142:143]
	v_pk_mul_f32 v[4:5], v[4:5], v[138:139]
	v_pk_mul_f32 v[2:3], v[2:3], v[136:137]
	v_pk_mul_f32 v[48:49], v[48:49], v[222:223]

; #define SBAR() __builtin_amdgcn_sched_barrier(0)
; template <int D0> __device__ __forceinline__ void pv_one(f32x16& od, int vb, bf16x8 pa0, bf16x8 pa1, bf16x8 pa2, bf16x8 pa3) {
;   const s16x4 l0 = tr_read<v_rd_off(D0, 0, 0)>(vb), h0 = tr_read<v_rd_off(D0, 0, 1)>(vb), l1 = tr_read<v_rd_off(D0, 1, 0)>(vb), h1 = tr_read<v_rd_off(D0, 1, 1)>(vb);
;   const s16x4 l2 = tr_read<v_rd_off(D0, 2, 0)>(vb), h2 = tr_read<v_rd_off(D0, 2, 1)>(vb), l3 = tr_read<v_rd_off(D0, 3, 0)>(vb), h3 = tr_read<v_rd_off(D0, 3, 1)>(vb);
;   asm volatile("s_waitcnt lgkmcnt(0)" ::: "memory"); SBAR();
;     ...
;   od = __builtin_amdgcn_mfma_f32_32x32x16_bf16(pa0, PK(l0, h0), od, 0, 0, 0);
;   od = __builtin_amdgcn_mfma_f32_32x32x16_bf16(pa1, PK(l1, h1), od, 0, 0, 0);
;   od = __builtin_amdgcn_mfma_f32_32x32x16_bf16(pa2, PK(l2, h2), od, 0, 0, 0);
;   od = __builtin_amdgcn_mfma_f32_32x32x16_bf16(pa3, PK(l3, h3), od, 0, 0, 0);
;     ...
; }
; __device__ __forceinline__ void pv_d0(f32x16* o, int vb, bf16x8 pa0, bf16x8 pa1, bf16x8 pa2, bf16x8 pa3) {
;   pv_one<0>(o[0], vb, pa0, pa1, pa2, pa3); pv_one<1>(o[1], vb, pa0, pa1, pa2, pa3); pv_one<2>(o[2], vb, pa0, pa1, pa2, pa3); pv_one<3>(o[3], vb, pa0, pa1, pa2, pa3);
.LBB0_666:
	ds_read_b64_tr_b16 v[220:221], v151 offset:0
	ds_read_b64_tr_b16 v[222:223], v151 offset:0x800
	ds_read_b64_tr_b16 v[224:225], v151 offset:0x1000
	ds_read_b64_tr_b16 v[226:227], v151 offset:0x1800
	ds_read_b64_tr_b16 v[228:229], v151 offset:0x2000
	ds_read_b64_tr_b16 v[230:231], v151 offset:0x2800
	ds_read_b64_tr_b16 v[232:233], v151 offset:0x3000
	ds_read_b64_tr_b16 v[234:235], v151 offset:0x3800
	s_waitcnt lgkmcnt(6)
	s_nop 0
	v_mfma_f32_32x32x16_bf16 v[18:33], v[130:133], v[220:223], v[18:33]
	ds_read_b64_tr_b16 v[220:221], v151 offset:0x200
	ds_read_b64_tr_b16 v[222:223], v151 offset:0xa00
	s_waitcnt lgkmcnt(6)
	v_mfma_f32_32x32x16_bf16 v[18:33], v[134:137], v[224:227], v[18:33]
	ds_read_b64_tr_b16 v[224:225], v151 offset:0x1200
	ds_read_b64_tr_b16 v[226:227], v151 offset:0x1a00
	s_waitcnt lgkmcnt(6)
	v_mfma_f32_32x32x16_bf16 v[18:33], v[138:141], v[228:231], v[18:33]
	ds_read_b64_tr_b16 v[228:229], v151 offset:0x2200
	ds_read_b64_tr_b16 v[230:231], v151 offset:0x2a00
	s_waitcnt lgkmcnt(6)
	v_mfma_f32_32x32x16_bf16 v[18:33], v[142:145], v[232:235], v[18:33]
	ds_read_b64_tr_b16 v[232:233], v151 offset:0x3200
	ds_read_b64_tr_b16 v[234:235], v151 offset:0x3a00
	s_waitcnt lgkmcnt(6)
	v_mfma_f32_32x32x16_bf16 v[50:65], v[130:133], v[220:223], v[50:65]
	ds_read_b64_tr_b16 v[220:221], v151 offset:0x400
	ds_read_b64_tr_b16 v[222:223], v151 offset:0xc00
	s_waitcnt lgkmcnt(6)
	v_mfma_f32_32x32x16_bf16 v[50:65], v[134:137], v[224:227], v[50:65]
	ds_read_b64_tr_b16 v[224:225], v151 offset:0x1400
	ds_read_b64_tr_b16 v[226:227], v151 offset:0x1c00
	s_waitcnt lgkmcnt(6)
	v_mfma_f32_32x32x16_bf16 v[50:65], v[138:141], v[228:231], v[50:65]
	ds_read_b64_tr_b16 v[228:229], v151 offset:0x2400
	ds_read_b64_tr_b16 v[230:231], v151 offset:0x2c00
	s_waitcnt lgkmcnt(6)
	v_mfma_f32_32x32x16_bf16 v[50:65], v[142:145], v[232:235], v[50:65]
	ds_read_b64_tr_b16 v[232:233], v151 offset:0x3400
	ds_read_b64_tr_b16 v[234:235], v151 offset:0x3c00
	s_waitcnt lgkmcnt(6)
	v_mfma_f32_32x32x16_bf16 v[2:17], v[130:133], v[220:223], v[2:17]
	ds_read_b64_tr_b16 v[220:221], v151 offset:0x600
	ds_read_b64_tr_b16 v[222:223], v151 offset:0xe00
	s_waitcnt lgkmcnt(6)
	v_mfma_f32_32x32x16_bf16 v[2:17], v[134:137], v[224:227], v[2:17]
	ds_read_b64_tr_b16 v[224:225], v151 offset:0x1600
	ds_read_b64_tr_b16 v[226:227], v151 offset:0x1e00
	s_waitcnt lgkmcnt(6)
	v_mfma_f32_32x32x16_bf16 v[2:17], v[138:141], v[228:231], v[2:17]
	ds_read_b64_tr_b16 v[228:229], v151 offset:0x2600
	ds_read_b64_tr_b16 v[230:231], v151 offset:0x2e00
	s_waitcnt lgkmcnt(6)
	v_mfma_f32_32x32x16_bf16 v[2:17], v[142:145], v[232:235], v[2:17]
	ds_read_b64_tr_b16 v[232:233], v151 offset:0x3600
	ds_read_b64_tr_b16 v[234:235], v151 offset:0x3e00
	s_waitcnt lgkmcnt(6)
	v_mfma_f32_32x32x16_bf16 v[34:49], v[130:133], v[220:223], v[34:49]
	v_max_f32_e32 v130, v83, v83
	v_max_f32_e32 v131, v82, v82
	v_max_f32_e32 v130, v131, v130
	v_max3_f32 v130, v130, v84, v85
	v_max3_f32 v130, v130, v86, v87
	v_max3_f32 v130, v130, v88, v89
	v_max3_f32 v130, v130, v90, v91
	v_max3_f32 v130, v130, v92, v93
	v_max3_f32 v130, v130, v94, v95
	s_waitcnt lgkmcnt(4)
	v_mfma_f32_32x32x16_bf16 v[34:49], v[134:137], v[224:227], v[34:49]
	v_max3_f32 v130, v130, v96, v97
	v_max3_f32 v130, v130, v66, v67
	v_max3_f32 v130, v130, v68, v69
	v_max3_f32 v130, v130, v70, v71
	v_max3_f32 v130, v130, v72, v73
	v_max3_f32 v130, v130, v74, v75
	v_max3_f32 v130, v130, v76, v77
	v_max3_f32 v130, v130, v78, v79
	s_waitcnt lgkmcnt(2)
	v_mfma_f32_32x32x16_bf16 v[34:49], v[138:141], v[228:231], v[34:49]
	v_max3_f32 v130, v130, v80, v81
	v_mov_b32_e32 v131, v130
	s_nop 1
	v_permlane32_swap_b32_e32 v130, v131
	v_max_f32_e32 v131, v131, v131
	v_max_f32_e32 v130, v130, v130
	v_max_f32_e32 v130, v130, v131
	v_sub_f32_e32 v131, v130, v215
	s_mov_b32 s2, 0x42b504f3
	v_cmp_ge_f32_e32 vcc, s2, v131
	v_max_f32_e32 v131, v215, v215
	v_max_f32_e32 v131, v131, v130
	s_waitcnt lgkmcnt(0)
	v_mfma_f32_32x32x16_bf16 v[34:49], v[142:145], v[232:235], v[34:49]
	v_sub_f32_e32 v130, v215, v131
	v_mul_f32_e32 v130, 0x3e0293ee, v130
	v_exp_f32_e32 v130, v130
	s_cmp_eq_u64 vcc, exec
	s_cselect_b64 s[2:3], -1, 0
	s_waitcnt vmcnt(4)
	v_cndmask_b32_e64 v130, v130, 1.0, s[2:3]
	v_cmp_gt_f32_e32 vcc, 1.0, v130
	v_mov_b64_e32 v[244:245], v[114:115]
	v_mov_b64_e32 v[246:247], v[116:117]
	v_mov_b64_e32 v[194:195], v[126:127]
	v_mov_b64_e32 v[196:197], v[128:129]
	ds_write_b128 v177, v[118:121] offset:49152
	ds_write_b128 v208, v[122:125] offset:49152
	s_cbranch_vccz .LBB0_670
	s_and_saveexec_b64 s[6:7], s[0:1]
	ds_write_b32 v149, v130 offset:128
	s_or_b64 exec, exec, s[6:7]
	s_waitcnt lgkmcnt(0)
	v_add_u32_e32 v126, v148, v0
	ds_read_b128 v[114:117], v126 offset:128
	ds_read_b128 v[118:121], v126 offset:160
	ds_read_b128 v[122:125], v126 offset:192
	ds_read_b128 v[126:129], v126 offset:224
	s_waitcnt lgkmcnt(3)
	v_pk_mul_f32 v[50:51], v[114:115], v[50:51]
	v_pk_mul_f32 v[52:53], v[52:53], v[116:117]
	s_waitcnt lgkmcnt(2)
	v_pk_mul_f32 v[54:55], v[54:55], v[118:119]
	v_pk_mul_f32 v[56:57], v[56:57], v[120:121]
	s_waitcnt lgkmcnt(1)
	v_pk_mul_f32 v[58:59], v[58:59], v[122:123]
	v_pk_mul_f32 v[60:61], v[60:61], v[124:125]
	s_waitcnt lgkmcnt(0)
	v_pk_mul_f32 v[62:63], v[62:63], v[126:127]
	v_pk_mul_f32 v[30:31], v[30:31], v[126:127]
	v_pk_mul_f32 v[26:27], v[26:27], v[122:123]
	v_pk_mul_f32 v[22:23], v[22:23], v[118:119]
	v_pk_mul_f32 v[32:33], v[32:33], v[128:129]
	v_pk_mul_f32 v[28:29], v[28:29], v[124:125]
	v_pk_mul_f32 v[24:25], v[24:25], v[120:121]
	v_pk_mul_f32 v[20:21], v[20:21], v[116:117]
	v_pk_mul_f32 v[18:19], v[18:19], v[114:115]
	v_pk_mul_f32 v[64:65], v[64:65], v[128:129]
	v_pk_mul_f32 v[34:35], v[114:115], v[34:35]
	v_pk_mul_f32 v[36:37], v[36:37], v[116:117]
	v_pk_mul_f32 v[38:39], v[38:39], v[118:119]
	v_pk_mul_f32 v[40:41], v[40:41], v[120:121]
	v_pk_mul_f32 v[42:43], v[42:43], v[122:123]
	v_pk_mul_f32 v[44:45], v[44:45], v[124:125]
	v_pk_mul_f32 v[46:47], v[46:47], v[126:127]
	v_pk_mul_f32 v[14:15], v[14:15], v[126:127]
	v_pk_mul_f32 v[10:11], v[10:11], v[122:123]
	v_pk_mul_f32 v[6:7], v[6:7], v[118:119]
	v_pk_mul_f32 v[16:17], v[16:17], v[128:129]
	v_pk_mul_f32 v[12:13], v[12:13], v[124:125]
	v_pk_mul_f32 v[8:9], v[8:9], v[120:121]
	v_pk_mul_f32 v[4:5], v[4:5], v[116:117]
	v_pk_mul_f32 v[2:3], v[2:3], v[114:115]
	v_pk_mul_f32 v[48:49], v[48:49], v[128:129]

; __device__ __forceinline__ void finishSM(f32x16& p0, f32x16& p1, float alpha, float& l_reg, bf16x8& pa0, bf16x8& pa1, bf16x8& pa2, bf16x8& pa3) {
; #pragma unroll
;   for (int r = 0; r < 16; ++r) p1[r] = __builtin_amdgcn_exp2f(p1[r]);
;   float ps = 0;
; #pragma unroll
;   for (int r = 0; r < 16; ++r) ps += p0[r];
; #pragma unroll
;   for (int r = 0; r < 16; ++r) ps += p1[r];
;   { auto rr = __builtin_amdgcn_permlane32_swap(__float_as_uint(ps), __float_as_uint(ps), false, false);
;     ps = __uint_as_float(rr[0]) + __uint_as_float(rr[1]); }
;   l_reg = l_reg * alpha + ps;
;     ...
;   PK4(p0, 0, pa0); PK4(p0, 8, pa1); PK4(p1, 0, pa2); PK4(p1, 8, pa3);
; template <int DK, bool QL>
; __device__ __forceinline__ void qkt(f32x16& p0, f32x16& p1, const bf16* Ks, const bf16x8* qr, const char* ql, int r32, int hi) {
;   p0 = f32x16{}; p1 = f32x16{};
; #pragma unroll
;   for (int d0 = 0; d0 < DK / 16; ++d0) { int cb = (d0 * 16 + hi * 8) * 2;
;     const bf16x8 qv = QL ? *reinterpret_cast<const bf16x8*>(ql + d0 * 1024) : qr[d0];
;     bf16x8 b0 = *reinterpret_cast<const bf16x8*>((const char*)Ks + kswz<DK>(r32, cb));
;     bf16x8 b1 = *reinterpret_cast<const bf16x8*>((const char*)Ks + kswz<DK>(32 + r32, cb));
;     p0 = __builtin_amdgcn_mfma_f32_32x32x16_bf16(b0, qv, p0, 0, 0, 0);
;     p1 = __builtin_amdgcn_mfma_f32_32x32x16_bf16(b1, qv, p1, 0, 0, 0); }
.LBB0_682:
	ds_read_b128 v[66:69], v212 offset:49152
	ds_read_b128 v[70:73], v212 offset:53248
	v_exp_f32_e32 v143, v138
	v_add_f32_e32 v138, 0, v177
	v_add_f32_e32 v138, v226, v138
	s_waitcnt lgkmcnt(1)
	v_mfma_f32_32x32x16_bf16 v[82:97], v[66:69], v[110:113], 0
	v_add_f32_e32 v138, v161, v138
	v_add_f32_e32 v138, v223, v138
	v_add_f32_e32 v138, v153, v138
	ds_read_b128 v[228:231], v216 offset:49152
	ds_read_b128 v[232:235], v216 offset:53248
	v_add_f32_e32 v138, v176, v138
	v_add_f32_e32 v138, v152, v138
	v_add_f32_e32 v138, v160, v138
	s_waitcnt lgkmcnt(2)
	v_mfma_f32_32x32x16_bf16 v[66:81], v[70:73], v[110:113], 0
	v_add_f32_e32 v138, v149, v138
	v_add_f32_e32 v138, v151, v138
	v_add_f32_e32 v138, v147, v138
	v_add_f32_e32 v138, v150, v138
	v_add_f32_e32 v138, v145, v138
	v_exp_f32_e32 v164, v139
	v_add_f32_e32 v138, v148, v138
	s_waitcnt lgkmcnt(1)
	v_mfma_f32_32x32x16_bf16 v[82:97], v[228:231], v[106:109], v[82:97]
	v_exp_f32_e32 v136, v136
	v_add_f32_e32 v138, v144, v138
	v_exp_f32_e32 v137, v137
	v_add_f32_e32 v138, v146, v138
	v_exp_f32_e32 v130, v130
	v_add_f32_e32 v138, v143, v138
	v_exp_f32_e32 v131, v131
	s_waitcnt lgkmcnt(0)
	v_mfma_f32_32x32x16_bf16 v[66:81], v[232:235], v[106:109], v[66:81]
	ds_read_b128 v[228:231], v217 offset:49152
	ds_read_b128 v[232:235], v217 offset:53248
	v_add_f32_e32 v138, v164, v138
	v_exp_f32_e32 v128, v128
	v_add_f32_e32 v138, v136, v138
	v_exp_f32_e32 v129, v129
	v_add_f32_e32 v138, v137, v138
	v_exp_f32_e32 v126, v126
	s_waitcnt lgkmcnt(1)
	v_mfma_f32_32x32x16_bf16 v[82:97], v[228:231], v[98:101], v[82:97]
	v_add_f32_e32 v138, v130, v138
	v_exp_f32_e32 v127, v127
	v_add_f32_e32 v138, v131, v138
	v_exp_f32_e32 v165, v140
	v_add_f32_e32 v138, v128, v138
	v_exp_f32_e32 v166, v141
	v_add_f32_e32 v138, v129, v138
	s_waitcnt lgkmcnt(0)
	v_mfma_f32_32x32x16_bf16 v[66:81], v[232:235], v[98:101], v[66:81]
	ds_read_b128 v[228:231], v218 offset:49152
	ds_read_b128 v[232:235], v218 offset:53248
	v_exp_f32_e32 v134, v134
	v_add_f32_e32 v138, v126, v138
	v_exp_f32_e32 v135, v135
	v_add_f32_e32 v138, v127, v138
	v_exp_f32_e32 v132, v132
	v_add_f32_e32 v138, v165, v138
	s_waitcnt lgkmcnt(1)
	v_mfma_f32_32x32x16_bf16 v[82:97], v[228:231], v[102:105], v[82:97]
	v_exp_f32_e32 v133, v133
	v_add_f32_e32 v138, v166, v138
	v_add_f32_e32 v138, v134, v138
	v_add_f32_e32 v138, v135, v138
	v_add_f32_e32 v138, v132, v138
	v_add_f32_e32 v220, v133, v138
	v_mov_b32_e32 v221, v220
	s_waitcnt lgkmcnt(0)
	v_mfma_f32_32x32x16_bf16 v[66:81], v[232:235], v[102:105], v[66:81]
	v_cvt_pk_bf16_f32 v138, v177, v226
	v_cvt_pk_bf16_f32 v139, v161, v223
	v_cvt_pk_bf16_f32 v140, v153, v176
	v_cvt_pk_bf16_f32 v141, v152, v160
	v_cvt_pk_bf16_f32 v222, v149, v151
	v_cvt_pk_bf16_f32 v223, v147, v150
	v_cvt_pk_bf16_f32 v224, v145, v148
	v_permlane32_swap_b32_e32 v220, v221
	v_permlane32_swap_b32_e32 v138, v140
	v_cvt_pk_bf16_f32 v225, v144, v146
	v_permlane32_swap_b32_e32 v222, v224
	v_cvt_pk_bf16_f32 v144, v143, v164
	v_cvt_pk_bf16_f32 v145, v136, v137
	v_cvt_pk_bf16_f32 v146, v130, v131
	v_cvt_pk_bf16_f32 v147, v128, v129
	v_cvt_pk_bf16_f32 v148, v126, v127
	v_cvt_pk_bf16_f32 v149, v165, v166
	v_cvt_pk_bf16_f32 v150, v134, v135
	v_cvt_pk_bf16_f32 v151, v132, v133
	v_permlane32_swap_b32_e32 v139, v141
	v_permlane32_swap_b32_e32 v223, v225
	v_permlane32_swap_b32_e32 v144, v146
	v_permlane32_swap_b32_e32 v145, v147
	v_permlane32_swap_b32_e32 v148, v150
	v_permlane32_swap_b32_e32 v149, v151
	v_readlane_b32 s2, v254, 32
	v_readlane_b32 s3, v254, 33
	s_mov_b32 s4, 0xe0e0000
	s_mov_b32 s5, 0xe130000
	v_lshl_add_u64 v[160:161], v[156:157], 0, s[2:3]
	v_add_co_u32_e32 v126, vcc, s4, v160
	v_lshl_add_u64 v[176:177], v[158:159], 0, s[2:3]
	s_nop 0
	v_addc_co_u32_e32 v127, vcc, 0, v161, vcc
	v_add_co_u32_e32 v130, vcc, s5, v160
	s_nop 1
	v_addc_co_u32_e32 v131, vcc, 0, v161, vcc
	v_add_co_u32_e32 v134, vcc, s4, v176
	global_load_dwordx4 v[126:129], v[126:127], off offset:2048
	s_nop 0
	global_load_dwordx4 v[130:133], v[130:131], off offset:2048
	v_addc_co_u32_e32 v135, vcc, 0, v177, vcc
	global_load_dwordx4 v[134:137], v[134:135], off offset:1024
	ds_read_b64_tr_b16 v[226:227], v211 offset:0
	ds_read_b64_tr_b16 v[228:229], v211 offset:0x800
	ds_read_b64_tr_b16 v[230:231], v211 offset:0x1000
	ds_read_b64_tr_b16 v[232:233], v211 offset:0x1800
	ds_read_b64_tr_b16 v[234:235], v211 offset:0x2000
	ds_read_b64_tr_b16 v[236:237], v211 offset:0x2800
	ds_read_b64_tr_b16 v[238:239], v211 offset:0x3000
	ds_read_b64_tr_b16 v[240:241], v211 offset:0x3800
	s_waitcnt lgkmcnt(6)
	s_nop 0
	v_mfma_f32_32x32x16_bf16 v[18:33], v[138:141], v[226:229], v[18:33]
	ds_read_b64_tr_b16 v[226:227], v211 offset:0x200
	ds_read_b64_tr_b16 v[228:229], v211 offset:0xa00
	s_waitcnt lgkmcnt(6)
	v_mfma_f32_32x32x16_bf16 v[18:33], v[222:225], v[230:233], v[18:33]
	ds_read_b64_tr_b16 v[230:231], v211 offset:0x1200
	ds_read_b64_tr_b16 v[232:233], v211 offset:0x1a00
	s_waitcnt lgkmcnt(6)
	v_mfma_f32_32x32x16_bf16 v[18:33], v[144:147], v[234:237], v[18:33]
	ds_read_b64_tr_b16 v[234:235], v211 offset:0x2200
	ds_read_b64_tr_b16 v[236:237], v211 offset:0x2a00
	s_waitcnt lgkmcnt(6)
; #define SBAR() __builtin_amdgcn_sched_barrier(0)
; template <int D0> __device__ __forceinline__ void pv_one(f32x16& od, int vb, bf16x8 pa0, bf16x8 pa1, bf16x8 pa2, bf16x8 pa3) {
;   const s16x4 l0 = tr_read<v_rd_off(D0, 0, 0)>(vb), h0 = tr_read<v_rd_off(D0, 0, 1)>(vb), l1 = tr_read<v_rd_off(D0, 1, 0)>(vb), h1 = tr_read<v_rd_off(D0, 1, 1)>(vb);
;   const s16x4 l2 = tr_read<v_rd_off(D0, 2, 0)>(vb), h2 = tr_read<v_rd_off(D0, 2, 1)>(vb), l3 = tr_read<v_rd_off(D0, 3, 0)>(vb), h3 = tr_read<v_rd_off(D0, 3, 1)>(vb);
;   asm volatile("s_waitcnt lgkmcnt(0)" ::: "memory"); SBAR();
;     ...
;   od = __builtin_amdgcn_mfma_f32_32x32x16_bf16(pa0, PK(l0, h0), od, 0, 0, 0);
;   od = __builtin_amdgcn_mfma_f32_32x32x16_bf16(pa1, PK(l1, h1), od, 0, 0, 0);
;   od = __builtin_amdgcn_mfma_f32_32x32x16_bf16(pa2, PK(l2, h2), od, 0, 0, 0);
;   od = __builtin_amdgcn_mfma_f32_32x32x16_bf16(pa3, PK(l3, h3), od, 0, 0, 0);
;     ...
; }
; __device__ __forceinline__ void pv_d0(f32x16* o, int vb, bf16x8 pa0, bf16x8 pa1, bf16x8 pa2, bf16x8 pa3) {
;   pv_one<0>(o[0], vb, pa0, pa1, pa2, pa3); pv_one<1>(o[1], vb, pa0, pa1, pa2, pa3); pv_one<2>(o[2], vb, pa0, pa1, pa2, pa3); pv_one<3>(o[3], vb, pa0, pa1, pa2, pa3);
	v_mfma_f32_32x32x16_bf16 v[18:33], v[148:151], v[238:241], v[18:33]
	ds_read_b64_tr_b16 v[238:239], v211 offset:0x3200
	ds_read_b64_tr_b16 v[240:241], v211 offset:0x3a00
	s_waitcnt lgkmcnt(6)
	v_mfma_f32_32x32x16_bf16 v[2:17], v[138:141], v[226:229], v[2:17]
	ds_read_b64_tr_b16 v[226:227], v211 offset:0x400
	ds_read_b64_tr_b16 v[228:229], v211 offset:0xc00
	s_waitcnt lgkmcnt(6)
	v_mfma_f32_32x32x16_bf16 v[2:17], v[222:225], v[230:233], v[2:17]
	ds_read_b64_tr_b16 v[230:231], v211 offset:0x1400
	ds_read_b64_tr_b16 v[232:233], v211 offset:0x1c00
	s_waitcnt lgkmcnt(6)
	v_mfma_f32_32x32x16_bf16 v[2:17], v[144:147], v[234:237], v[2:17]
	ds_read_b64_tr_b16 v[234:235], v211 offset:0x2400
	ds_read_b64_tr_b16 v[236:237], v211 offset:0x2c00
	s_waitcnt lgkmcnt(6)
	v_mfma_f32_32x32x16_bf16 v[2:17], v[148:151], v[238:241], v[2:17]
	ds_read_b64_tr_b16 v[238:239], v211 offset:0x3400
	ds_read_b64_tr_b16 v[240:241], v211 offset:0x3c00
	s_waitcnt lgkmcnt(6)
	v_mfma_f32_32x32x16_bf16 v[50:65], v[138:141], v[226:229], v[50:65]
	ds_read_b64_tr_b16 v[226:227], v211 offset:0x600
	ds_read_b64_tr_b16 v[228:229], v211 offset:0xe00
	s_waitcnt lgkmcnt(6)
	v_mfma_f32_32x32x16_bf16 v[50:65], v[222:225], v[230:233], v[50:65]
	ds_read_b64_tr_b16 v[230:231], v211 offset:0x1600
	ds_read_b64_tr_b16 v[232:233], v211 offset:0x1e00
	s_waitcnt lgkmcnt(6)
	v_mfma_f32_32x32x16_bf16 v[50:65], v[144:147], v[234:237], v[50:65]
	ds_read_b64_tr_b16 v[234:235], v211 offset:0x2600
	ds_read_b64_tr_b16 v[236:237], v211 offset:0x2e00
	s_waitcnt lgkmcnt(6)
	v_mfma_f32_32x32x16_bf16 v[50:65], v[148:151], v[238:241], v[50:65]
	ds_read_b64_tr_b16 v[238:239], v211 offset:0x3600
	ds_read_b64_tr_b16 v[240:241], v211 offset:0x3e00
	s_waitcnt lgkmcnt(6)
	v_mfma_f32_32x32x16_bf16 v[34:49], v[138:141], v[226:229], v[34:49]
	v_max_f32_e32 v138, v83, v83
	v_max_f32_e32 v139, v82, v82
	v_max_f32_e32 v138, v139, v138
	v_max3_f32 v138, v138, v84, v85
	v_max3_f32 v138, v138, v86, v87
	v_max3_f32 v138, v138, v88, v89
	v_max3_f32 v138, v138, v90, v91
	v_max3_f32 v138, v138, v92, v93
	v_max3_f32 v138, v138, v94, v95
	s_waitcnt lgkmcnt(4)
	v_mfma_f32_32x32x16_bf16 v[34:49], v[222:225], v[230:233], v[34:49]
	v_max3_f32 v138, v138, v96, v97
	v_max3_f32 v138, v138, v66, v67
	v_max3_f32 v138, v138, v68, v69
	v_max3_f32 v138, v138, v70, v71
	v_max3_f32 v138, v138, v72, v73
	v_max3_f32 v138, v138, v74, v75
	v_max3_f32 v138, v138, v76, v77
	v_max3_f32 v138, v138, v78, v79
	s_waitcnt lgkmcnt(2)
	v_mfma_f32_32x32x16_bf16 v[34:49], v[144:147], v[234:237], v[34:49]
	v_max3_f32 v138, v138, v80, v81
	v_mov_b32_e32 v139, v138
	s_nop 1
	v_permlane32_swap_b32_e32 v138, v139
	v_max_f32_e32 v139, v139, v139
	v_max_f32_e32 v138, v138, v138
	v_max_f32_e32 v138, v138, v139
	v_sub_f32_e32 v139, v138, v142
	s_mov_b32 s2, 0x42800000
	v_cmp_ge_f32_e32 vcc, s2, v139
	v_max_f32_e32 v139, v142, v142
	v_max_f32_e32 v138, v139, v138
	s_waitcnt lgkmcnt(0)
	v_mfma_f32_32x32x16_bf16 v[34:49], v[148:151], v[238:241], v[34:49]
	v_sub_f32_e32 v139, v142, v138
	v_mul_f32_e32 v139, 0x3e38aa3b, v139
	v_exp_f32_e32 v139, v139
	s_cmp_eq_u64 vcc, exec
	s_cselect_b64 s[2:3], -1, 0
	s_waitcnt vmcnt(3)
	v_cndmask_b32_e64 v222, v139, 1.0, s[2:3]
	v_cmp_gt_f32_e32 vcc, 1.0, v222
	s_waitcnt vmcnt(3)
	ds_write_b128 v213, v[122:125] offset:32768
	s_cbranch_vccz .LBB0_686
	s_and_saveexec_b64 s[4:5], s[0:1]
	ds_write_b32 v208, v222 offset:128
	s_or_b64 exec, exec, s[4:5]
	s_waitcnt lgkmcnt(0)
	v_add_u32_e32 v139, v207, v0
	ds_read_b128 v[144:147], v139 offset:128
	ds_read_b128 v[148:151], v139 offset:160
	ds_read_b128 v[224:227], v139 offset:192
	ds_read_b128 v[228:231], v139 offset:224
	s_waitcnt lgkmcnt(3)
	v_pk_mul_f32 v[2:3], v[144:145], v[2:3]
	v_pk_mul_f32 v[4:5], v[4:5], v[146:147]
	s_waitcnt lgkmcnt(2)
	v_pk_mul_f32 v[6:7], v[6:7], v[148:149]
	v_pk_mul_f32 v[8:9], v[8:9], v[150:151]
	s_waitcnt lgkmcnt(1)
	v_pk_mul_f32 v[10:11], v[10:11], v[224:225]
	v_pk_mul_f32 v[12:13], v[12:13], v[226:227]
	s_waitcnt lgkmcnt(0)
	v_pk_mul_f32 v[14:15], v[14:15], v[228:229]
	v_pk_mul_f32 v[30:31], v[30:31], v[228:229]
	v_pk_mul_f32 v[26:27], v[26:27], v[224:225]
	v_pk_mul_f32 v[22:23], v[22:23], v[148:149]
	v_pk_mul_f32 v[32:33], v[32:33], v[230:231]
	v_pk_mul_f32 v[28:29], v[28:29], v[226:227]
	v_pk_mul_f32 v[24:25], v[24:25], v[150:151]
	v_pk_mul_f32 v[20:21], v[20:21], v[146:147]
	v_pk_mul_f32 v[18:19], v[18:19], v[144:145]
	v_pk_mul_f32 v[16:17], v[16:17], v[230:231]
	v_pk_mul_f32 v[34:35], v[144:145], v[34:35]
	v_pk_mul_f32 v[36:37], v[36:37], v[146:147]
	v_pk_mul_f32 v[38:39], v[38:39], v[148:149]
	v_pk_mul_f32 v[40:41], v[40:41], v[150:151]
	v_pk_mul_f32 v[42:43], v[42:43], v[224:225]
	v_pk_mul_f32 v[44:45], v[44:45], v[226:227]
	v_pk_mul_f32 v[46:47], v[46:47], v[228:229]
	v_pk_mul_f32 v[62:63], v[62:63], v[228:229]
	v_pk_mul_f32 v[58:59], v[58:59], v[224:225]
	v_pk_mul_f32 v[54:55], v[54:55], v[148:149]
	v_pk_mul_f32 v[64:65], v[64:65], v[230:231]
	v_pk_mul_f32 v[60:61], v[60:61], v[226:227]
	v_pk_mul_f32 v[56:57], v[56:57], v[150:151]
	v_pk_mul_f32 v[52:53], v[52:53], v[146:147]
	v_pk_mul_f32 v[50:51], v[50:51], v[144:145]
	v_pk_mul_f32 v[48:49], v[48:49], v[230:231]

; #define SBAR() __builtin_amdgcn_sched_barrier(0)
; template <int D0> __device__ __forceinline__ void pv_one(f32x16& od, int vb, bf16x8 pa0, bf16x8 pa1, bf16x8 pa2, bf16x8 pa3) {
;   const s16x4 l0 = tr_read<v_rd_off(D0, 0, 0)>(vb), h0 = tr_read<v_rd_off(D0, 0, 1)>(vb), l1 = tr_read<v_rd_off(D0, 1, 0)>(vb), h1 = tr_read<v_rd_off(D0, 1, 1)>(vb);
;   const s16x4 l2 = tr_read<v_rd_off(D0, 2, 0)>(vb), h2 = tr_read<v_rd_off(D0, 2, 1)>(vb), l3 = tr_read<v_rd_off(D0, 3, 0)>(vb), h3 = tr_read<v_rd_off(D0, 3, 1)>(vb);
;   asm volatile("s_waitcnt lgkmcnt(0)" ::: "memory"); SBAR();
;     ...
;   od = __builtin_amdgcn_mfma_f32_32x32x16_bf16(pa0, PK(l0, h0), od, 0, 0, 0);
;   od = __builtin_amdgcn_mfma_f32_32x32x16_bf16(pa1, PK(l1, h1), od, 0, 0, 0);
;   od = __builtin_amdgcn_mfma_f32_32x32x16_bf16(pa2, PK(l2, h2), od, 0, 0, 0);
;   od = __builtin_amdgcn_mfma_f32_32x32x16_bf16(pa3, PK(l3, h3), od, 0, 0, 0);
;     ...
; }
; __device__ __forceinline__ void pv_d0(f32x16* o, int vb, bf16x8 pa0, bf16x8 pa1, bf16x8 pa2, bf16x8 pa3) {
;   pv_one<0>(o[0], vb, pa0, pa1, pa2, pa3); pv_one<1>(o[1], vb, pa0, pa1, pa2, pa3); pv_one<2>(o[2], vb, pa0, pa1, pa2, pa3); pv_one<3>(o[3], vb, pa0, pa1, pa2, pa3);
.LBB0_688:
	ds_read_b64_tr_b16 v[226:227], v210 offset:0
	ds_read_b64_tr_b16 v[228:229], v210 offset:0x800
	ds_read_b64_tr_b16 v[230:231], v210 offset:0x1000
	ds_read_b64_tr_b16 v[232:233], v210 offset:0x1800
	ds_read_b64_tr_b16 v[234:235], v210 offset:0x2000
	ds_read_b64_tr_b16 v[236:237], v210 offset:0x2800
	ds_read_b64_tr_b16 v[238:239], v210 offset:0x3000
	ds_read_b64_tr_b16 v[240:241], v210 offset:0x3800
	s_waitcnt lgkmcnt(6)
	s_nop 0
	v_mfma_f32_32x32x16_bf16 v[18:33], v[138:141], v[226:229], v[18:33]
	ds_read_b64_tr_b16 v[226:227], v210 offset:0x200
	ds_read_b64_tr_b16 v[228:229], v210 offset:0xa00
	s_waitcnt lgkmcnt(6)
	v_mfma_f32_32x32x16_bf16 v[18:33], v[142:145], v[230:233], v[18:33]
	ds_read_b64_tr_b16 v[230:231], v210 offset:0x1200
	ds_read_b64_tr_b16 v[232:233], v210 offset:0x1a00
	s_waitcnt lgkmcnt(6)
	v_mfma_f32_32x32x16_bf16 v[18:33], v[146:149], v[234:237], v[18:33]
	ds_read_b64_tr_b16 v[234:235], v210 offset:0x2200
	ds_read_b64_tr_b16 v[236:237], v210 offset:0x2a00
	s_waitcnt lgkmcnt(6)
	v_mfma_f32_32x32x16_bf16 v[18:33], v[150:153], v[238:241], v[18:33]
	ds_read_b64_tr_b16 v[238:239], v210 offset:0x3200
	ds_read_b64_tr_b16 v[240:241], v210 offset:0x3a00
	s_waitcnt lgkmcnt(6)
	v_mfma_f32_32x32x16_bf16 v[2:17], v[138:141], v[226:229], v[2:17]
	ds_read_b64_tr_b16 v[226:227], v210 offset:0x400
	ds_read_b64_tr_b16 v[228:229], v210 offset:0xc00
	s_waitcnt lgkmcnt(6)
	v_mfma_f32_32x32x16_bf16 v[2:17], v[142:145], v[230:233], v[2:17]
	ds_read_b64_tr_b16 v[230:231], v210 offset:0x1400
	ds_read_b64_tr_b16 v[232:233], v210 offset:0x1c00
	s_waitcnt lgkmcnt(6)
	v_mfma_f32_32x32x16_bf16 v[2:17], v[146:149], v[234:237], v[2:17]
	ds_read_b64_tr_b16 v[234:235], v210 offset:0x2400
	ds_read_b64_tr_b16 v[236:237], v210 offset:0x2c00
	s_waitcnt lgkmcnt(6)
	v_mfma_f32_32x32x16_bf16 v[2:17], v[150:153], v[238:241], v[2:17]
	ds_read_b64_tr_b16 v[238:239], v210 offset:0x3400
	ds_read_b64_tr_b16 v[240:241], v210 offset:0x3c00
	s_waitcnt lgkmcnt(6)
	v_mfma_f32_32x32x16_bf16 v[50:65], v[138:141], v[226:229], v[50:65]
	ds_read_b64_tr_b16 v[226:227], v210 offset:0x600
	ds_read_b64_tr_b16 v[228:229], v210 offset:0xe00
	s_waitcnt lgkmcnt(6)
	v_mfma_f32_32x32x16_bf16 v[50:65], v[142:145], v[230:233], v[50:65]
	ds_read_b64_tr_b16 v[230:231], v210 offset:0x1600
	ds_read_b64_tr_b16 v[232:233], v210 offset:0x1e00
	s_waitcnt lgkmcnt(6)
	v_mfma_f32_32x32x16_bf16 v[50:65], v[146:149], v[234:237], v[50:65]
	ds_read_b64_tr_b16 v[234:235], v210 offset:0x2600
	ds_read_b64_tr_b16 v[236:237], v210 offset:0x2e00
	s_waitcnt lgkmcnt(6)
	v_mfma_f32_32x32x16_bf16 v[50:65], v[150:153], v[238:241], v[50:65]
	ds_read_b64_tr_b16 v[238:239], v210 offset:0x3600
	ds_read_b64_tr_b16 v[240:241], v210 offset:0x3e00
	s_waitcnt lgkmcnt(6)
	v_mfma_f32_32x32x16_bf16 v[34:49], v[138:141], v[226:229], v[34:49]
	v_max_f32_e32 v138, v83, v83
	v_max_f32_e32 v139, v82, v82
	v_max_f32_e32 v138, v139, v138
	v_max3_f32 v138, v138, v84, v85
	v_max3_f32 v138, v138, v86, v87
	v_max3_f32 v138, v138, v88, v89
	v_max3_f32 v138, v138, v90, v91
	v_max3_f32 v138, v138, v92, v93
	v_max3_f32 v138, v138, v94, v95
	s_waitcnt lgkmcnt(4)
	v_mfma_f32_32x32x16_bf16 v[34:49], v[142:145], v[230:233], v[34:49]
	v_max3_f32 v138, v138, v96, v97
	v_max3_f32 v138, v138, v66, v67
	v_max3_f32 v138, v138, v68, v69
	v_max3_f32 v138, v138, v70, v71
	v_max3_f32 v138, v138, v72, v73
	v_max3_f32 v138, v138, v74, v75
	v_max3_f32 v138, v138, v76, v77
	v_max3_f32 v138, v138, v78, v79
	s_waitcnt lgkmcnt(2)
	v_mfma_f32_32x32x16_bf16 v[34:49], v[146:149], v[234:237], v[34:49]
	v_max3_f32 v138, v138, v80, v81
	v_mov_b32_e32 v139, v138
	s_nop 1
	v_permlane32_swap_b32_e32 v138, v139
	v_max_f32_e32 v139, v139, v139
	v_max_f32_e32 v138, v138, v138
	v_max_f32_e32 v138, v138, v139
	v_sub_f32_e32 v139, v138, v223
	s_mov_b32 s2, 0x42800000
	v_cmp_ge_f32_e32 vcc, s2, v139
	v_max_f32_e32 v139, v223, v223
	v_max_f32_e32 v138, v139, v138
	s_waitcnt lgkmcnt(0)
	v_mfma_f32_32x32x16_bf16 v[34:49], v[150:153], v[238:241], v[34:49]
	v_sub_f32_e32 v139, v223, v138
	v_mul_f32_e32 v139, 0x3e38aa3b, v139
	v_exp_f32_e32 v139, v139
	s_cmp_eq_u64 vcc, exec
	s_cselect_b64 s[2:3], -1, 0
	s_waitcnt vmcnt(3)
	v_cndmask_b32_e64 v143, v139, 1.0, s[2:3]
	v_cmp_gt_f32_e32 vcc, 1.0, v143
	v_mov_b64_e32 v[182:183], v[126:127]
	v_mov_b64_e32 v[184:185], v[128:129]
	v_mov_b64_e32 v[194:195], v[130:131]
	v_mov_b64_e32 v[196:197], v[132:133]
	ds_write_b128 v213, v[134:137] offset:49152
	s_cbranch_vccz .LBB0_692
	s_and_saveexec_b64 s[6:7], s[0:1]
	ds_write_b32 v208, v143 offset:128
	s_or_b64 exec, exec, s[6:7]
	s_waitcnt lgkmcnt(0)
	v_add_u32_e32 v139, v207, v0
	ds_read_b128 v[126:129], v139 offset:128
	ds_read_b128 v[130:133], v139 offset:160
	ds_read_b128 v[134:137], v139 offset:224
	ds_read_b128 v[144:147], v139 offset:192
	s_waitcnt lgkmcnt(3)
	v_pk_mul_f32 v[50:51], v[126:127], v[50:51]
	v_pk_mul_f32 v[52:53], v[128:129], v[52:53]
	s_waitcnt lgkmcnt(2)
	v_pk_mul_f32 v[54:55], v[130:131], v[54:55]
	s_waitcnt lgkmcnt(1)
	v_pk_mul_f32 v[30:31], v[30:31], v[134:135]
	s_waitcnt lgkmcnt(0)
	v_pk_mul_f32 v[26:27], v[26:27], v[144:145]
	v_pk_mul_f32 v[22:23], v[22:23], v[130:131]
	v_pk_mul_f32 v[32:33], v[32:33], v[136:137]
	v_pk_mul_f32 v[28:29], v[28:29], v[146:147]
	v_pk_mul_f32 v[24:25], v[24:25], v[132:133]
	v_pk_mul_f32 v[20:21], v[20:21], v[128:129]
	v_pk_mul_f32 v[18:19], v[18:19], v[126:127]
	v_pk_mul_f32 v[14:15], v[134:135], v[14:15]
	v_pk_mul_f32 v[10:11], v[144:145], v[10:11]
	v_pk_mul_f32 v[6:7], v[130:131], v[6:7]
	v_pk_mul_f32 v[16:17], v[136:137], v[16:17]
	v_pk_mul_f32 v[12:13], v[146:147], v[12:13]
	v_pk_mul_f32 v[8:9], v[132:133], v[8:9]
	v_pk_mul_f32 v[4:5], v[128:129], v[4:5]
	v_pk_mul_f32 v[2:3], v[126:127], v[2:3]
	v_pk_mul_f32 v[56:57], v[132:133], v[56:57]
	v_pk_mul_f32 v[34:35], v[126:127], v[34:35]
	v_pk_mul_f32 v[36:37], v[36:37], v[128:129]
	v_pk_mul_f32 v[38:39], v[38:39], v[130:131]
	v_pk_mul_f32 v[40:41], v[40:41], v[132:133]
	v_pk_mul_f32 v[58:59], v[58:59], v[144:145]
	v_pk_mul_f32 v[42:43], v[42:43], v[144:145]
	v_pk_mul_f32 v[60:61], v[60:61], v[146:147]
	v_pk_mul_f32 v[44:45], v[44:45], v[146:147]
	v_pk_mul_f32 v[62:63], v[62:63], v[134:135]
	v_pk_mul_f32 v[46:47], v[46:47], v[134:135]
	v_pk_mul_f32 v[64:65], v[64:65], v[136:137]
	v_pk_mul_f32 v[48:49], v[48:49], v[136:137]

; __device__ __forceinline__ void finishSM(f32x16& p0, f32x16& p1, float alpha, float& l_reg, bf16x8& pa0, bf16x8& pa1, bf16x8& pa2, bf16x8& pa3) {
; #pragma unroll
;   for (int r = 0; r < 16; ++r) p1[r] = __builtin_amdgcn_exp2f(p1[r]);
;   float ps = 0;
; #pragma unroll
;   for (int r = 0; r < 16; ++r) ps += p0[r];
; #pragma unroll
;   for (int r = 0; r < 16; ++r) ps += p1[r];
;   { auto rr = __builtin_amdgcn_permlane32_swap(__float_as_uint(ps), __float_as_uint(ps), false, false);
;     ps = __uint_as_float(rr[0]) + __uint_as_float(rr[1]); }
;   l_reg = l_reg * alpha + ps;
;     ...
;   PK4(p0, 0, pa0); PK4(p0, 8, pa1); PK4(p1, 0, pa2); PK4(p1, 8, pa3);
; template <int DK, bool QL>
; __device__ __forceinline__ void qkt(f32x16& p0, f32x16& p1, const bf16* Ks, const bf16x8* qr, const char* ql, int r32, int hi) {
;   p0 = f32x16{}; p1 = f32x16{};
; #pragma unroll
;   for (int d0 = 0; d0 < DK / 16; ++d0) { int cb = (d0 * 16 + hi * 8) * 2;
;     const bf16x8 qv = QL ? *reinterpret_cast<const bf16x8*>(ql + d0 * 1024) : qr[d0];
;     bf16x8 b0 = *reinterpret_cast<const bf16x8*>((const char*)Ks + kswz<DK>(r32, cb));
;     bf16x8 b1 = *reinterpret_cast<const bf16x8*>((const char*)Ks + kswz<DK>(32 + r32, cb));
;     p0 = __builtin_amdgcn_mfma_f32_32x32x16_bf16(b0, qv, p0, 0, 0, 0);
;     p1 = __builtin_amdgcn_mfma_f32_32x32x16_bf16(b1, qv, p1, 0, 0, 0); }
.LBB0_701:
	ds_read_b128 v[66:69], v215 offset:49152
	ds_read_b128 v[70:73], v215 offset:53248
	v_exp_f32_e32 v143, v138
	v_add_f32_e32 v138, 0, v177
	v_add_f32_e32 v138, v226, v138
	s_waitcnt lgkmcnt(1)
	v_mfma_f32_32x32x16_bf16 v[82:97], v[66:69], v[110:113], 0
	v_add_f32_e32 v138, v161, v138
	v_add_f32_e32 v138, v223, v138
	v_add_f32_e32 v138, v153, v138
	ds_read_b128 v[228:231], v216 offset:49152
	ds_read_b128 v[232:235], v216 offset:53248
	v_add_f32_e32 v138, v176, v138
	v_add_f32_e32 v138, v152, v138
	v_add_f32_e32 v138, v160, v138
	s_waitcnt lgkmcnt(2)
	v_mfma_f32_32x32x16_bf16 v[66:81], v[70:73], v[110:113], 0
	v_add_f32_e32 v138, v149, v138
	v_add_f32_e32 v138, v151, v138
	v_add_f32_e32 v138, v147, v138
	v_add_f32_e32 v138, v150, v138
	v_add_f32_e32 v138, v145, v138
	v_exp_f32_e32 v164, v139
	v_add_f32_e32 v138, v148, v138
	s_waitcnt lgkmcnt(1)
	v_mfma_f32_32x32x16_bf16 v[82:97], v[228:231], v[106:109], v[82:97]
	v_exp_f32_e32 v136, v136
	v_add_f32_e32 v138, v144, v138
	v_exp_f32_e32 v137, v137
	v_add_f32_e32 v138, v146, v138
	v_exp_f32_e32 v130, v130
	v_add_f32_e32 v138, v143, v138
	v_exp_f32_e32 v131, v131
	s_waitcnt lgkmcnt(0)
	v_mfma_f32_32x32x16_bf16 v[66:81], v[232:235], v[106:109], v[66:81]
	ds_read_b128 v[228:231], v217 offset:49152
	ds_read_b128 v[232:235], v217 offset:53248
	v_add_f32_e32 v138, v164, v138
	v_exp_f32_e32 v128, v128
	v_add_f32_e32 v138, v136, v138
	v_exp_f32_e32 v129, v129
	v_add_f32_e32 v138, v137, v138
	v_exp_f32_e32 v126, v126
	s_waitcnt lgkmcnt(1)
	v_mfma_f32_32x32x16_bf16 v[82:97], v[228:231], v[102:105], v[82:97]
	v_add_f32_e32 v138, v130, v138
	v_exp_f32_e32 v127, v127
	v_add_f32_e32 v138, v131, v138
	v_exp_f32_e32 v165, v140
	v_add_f32_e32 v138, v128, v138
	v_exp_f32_e32 v166, v141
	v_add_f32_e32 v138, v129, v138
	s_waitcnt lgkmcnt(0)
	v_mfma_f32_32x32x16_bf16 v[66:81], v[232:235], v[102:105], v[66:81]
	ds_read_b128 v[228:231], v218 offset:49152
	ds_read_b128 v[232:235], v218 offset:53248
	v_exp_f32_e32 v134, v134
	v_add_f32_e32 v138, v126, v138
	v_exp_f32_e32 v135, v135
	v_add_f32_e32 v138, v127, v138
	v_exp_f32_e32 v132, v132
	v_add_f32_e32 v138, v165, v138
	s_waitcnt lgkmcnt(1)
	v_mfma_f32_32x32x16_bf16 v[82:97], v[228:231], v[98:101], v[82:97]
	v_exp_f32_e32 v133, v133
	v_add_f32_e32 v138, v166, v138
	v_add_f32_e32 v138, v134, v138
	v_add_f32_e32 v138, v135, v138
	v_add_f32_e32 v138, v132, v138
	v_add_f32_e32 v220, v133, v138
	v_mov_b32_e32 v221, v220
	s_waitcnt lgkmcnt(0)
	v_mfma_f32_32x32x16_bf16 v[66:81], v[232:235], v[98:101], v[66:81]
	v_cvt_pk_bf16_f32 v138, v177, v226
	v_cvt_pk_bf16_f32 v139, v161, v223
	v_cvt_pk_bf16_f32 v140, v153, v176
	v_cvt_pk_bf16_f32 v141, v152, v160
	v_cvt_pk_bf16_f32 v222, v149, v151
	v_cvt_pk_bf16_f32 v223, v147, v150
	v_cvt_pk_bf16_f32 v224, v145, v148
	v_permlane32_swap_b32_e32 v220, v221
	v_permlane32_swap_b32_e32 v138, v140
	v_cvt_pk_bf16_f32 v225, v144, v146
	v_permlane32_swap_b32_e32 v222, v224
	v_cvt_pk_bf16_f32 v144, v143, v164
	v_cvt_pk_bf16_f32 v145, v136, v137
	v_cvt_pk_bf16_f32 v146, v130, v131
	v_cvt_pk_bf16_f32 v147, v128, v129
	v_cvt_pk_bf16_f32 v148, v126, v127
	v_cvt_pk_bf16_f32 v149, v165, v166
	v_cvt_pk_bf16_f32 v150, v134, v135
	v_cvt_pk_bf16_f32 v151, v132, v133
	v_permlane32_swap_b32_e32 v139, v141
	v_permlane32_swap_b32_e32 v223, v225
	v_permlane32_swap_b32_e32 v144, v146
	v_permlane32_swap_b32_e32 v145, v147
	v_permlane32_swap_b32_e32 v148, v150
	v_permlane32_swap_b32_e32 v149, v151
	v_readlane_b32 s2, v254, 32
	v_readlane_b32 s3, v254, 33
	s_mov_b32 s4, 0xe0e0000
	s_mov_b32 s5, 0xe130000
	v_lshl_add_u64 v[160:161], v[156:157], 0, s[2:3]
	v_add_co_u32_e32 v126, vcc, s4, v160
	v_lshl_add_u64 v[176:177], v[158:159], 0, s[2:3]
	s_nop 0
	v_addc_co_u32_e32 v127, vcc, 0, v161, vcc
	v_add_co_u32_e32 v130, vcc, s5, v160
	s_nop 1
	v_addc_co_u32_e32 v131, vcc, 0, v161, vcc
	v_add_co_u32_e32 v134, vcc, s4, v176
	global_load_dwordx4 v[126:129], v[126:127], off offset:2048
	s_nop 0
	global_load_dwordx4 v[130:133], v[130:131], off offset:2048
	v_addc_co_u32_e32 v135, vcc, 0, v177, vcc
	global_load_dwordx4 v[134:137], v[134:135], off offset:1152
	ds_read_b64_tr_b16 v[226:227], v211 offset:0
	ds_read_b64_tr_b16 v[228:229], v211 offset:0x800
	ds_read_b64_tr_b16 v[230:231], v211 offset:0x1000
	ds_read_b64_tr_b16 v[232:233], v211 offset:0x1800
	ds_read_b64_tr_b16 v[234:235], v211 offset:0x2000
	ds_read_b64_tr_b16 v[236:237], v211 offset:0x2800
	ds_read_b64_tr_b16 v[238:239], v211 offset:0x3000
	ds_read_b64_tr_b16 v[240:241], v211 offset:0x3800
	s_waitcnt lgkmcnt(6)
	s_nop 0
	v_mfma_f32_32x32x16_bf16 v[2:17], v[138:141], v[226:229], v[2:17]
	ds_read_b64_tr_b16 v[226:227], v211 offset:0x200
	ds_read_b64_tr_b16 v[228:229], v211 offset:0xa00
	s_waitcnt lgkmcnt(6)
	v_mfma_f32_32x32x16_bf16 v[2:17], v[222:225], v[230:233], v[2:17]
	ds_read_b64_tr_b16 v[230:231], v211 offset:0x1200
	ds_read_b64_tr_b16 v[232:233], v211 offset:0x1a00
	s_waitcnt lgkmcnt(6)
	v_mfma_f32_32x32x16_bf16 v[2:17], v[144:147], v[234:237], v[2:17]
	ds_read_b64_tr_b16 v[234:235], v211 offset:0x2200
	ds_read_b64_tr_b16 v[236:237], v211 offset:0x2a00
	s_waitcnt lgkmcnt(6)
; #define SBAR() __builtin_amdgcn_sched_barrier(0)
; template <int D0> __device__ __forceinline__ void pv_one(f32x16& od, int vb, bf16x8 pa0, bf16x8 pa1, bf16x8 pa2, bf16x8 pa3) {
;   const s16x4 l0 = tr_read<v_rd_off(D0, 0, 0)>(vb), h0 = tr_read<v_rd_off(D0, 0, 1)>(vb), l1 = tr_read<v_rd_off(D0, 1, 0)>(vb), h1 = tr_read<v_rd_off(D0, 1, 1)>(vb);
;   const s16x4 l2 = tr_read<v_rd_off(D0, 2, 0)>(vb), h2 = tr_read<v_rd_off(D0, 2, 1)>(vb), l3 = tr_read<v_rd_off(D0, 3, 0)>(vb), h3 = tr_read<v_rd_off(D0, 3, 1)>(vb);
;   asm volatile("s_waitcnt lgkmcnt(0)" ::: "memory"); SBAR();
;     ...
;   od = __builtin_amdgcn_mfma_f32_32x32x16_bf16(pa0, PK(l0, h0), od, 0, 0, 0);
;   od = __builtin_amdgcn_mfma_f32_32x32x16_bf16(pa1, PK(l1, h1), od, 0, 0, 0);
;   od = __builtin_amdgcn_mfma_f32_32x32x16_bf16(pa2, PK(l2, h2), od, 0, 0, 0);
;   od = __builtin_amdgcn_mfma_f32_32x32x16_bf16(pa3, PK(l3, h3), od, 0, 0, 0);
;     ...
; }
; __device__ __forceinline__ void pv_d0(f32x16* o, int vb, bf16x8 pa0, bf16x8 pa1, bf16x8 pa2, bf16x8 pa3) {
;   pv_one<0>(o[0], vb, pa0, pa1, pa2, pa3); pv_one<1>(o[1], vb, pa0, pa1, pa2, pa3); pv_one<2>(o[2], vb, pa0, pa1, pa2, pa3); pv_one<3>(o[3], vb, pa0, pa1, pa2, pa3);
	v_mfma_f32_32x32x16_bf16 v[2:17], v[148:151], v[238:241], v[2:17]
	ds_read_b64_tr_b16 v[238:239], v211 offset:0x3200
	ds_read_b64_tr_b16 v[240:241], v211 offset:0x3a00
	s_waitcnt lgkmcnt(6)
	v_mfma_f32_32x32x16_bf16 v[50:65], v[138:141], v[226:229], v[50:65]
	ds_read_b64_tr_b16 v[226:227], v211 offset:0x400
	ds_read_b64_tr_b16 v[228:229], v211 offset:0xc00
	s_waitcnt lgkmcnt(6)
	v_mfma_f32_32x32x16_bf16 v[50:65], v[222:225], v[230:233], v[50:65]
	ds_read_b64_tr_b16 v[230:231], v211 offset:0x1400
	ds_read_b64_tr_b16 v[232:233], v211 offset:0x1c00
	s_waitcnt lgkmcnt(6)
	v_mfma_f32_32x32x16_bf16 v[50:65], v[144:147], v[234:237], v[50:65]
	ds_read_b64_tr_b16 v[234:235], v211 offset:0x2400
	ds_read_b64_tr_b16 v[236:237], v211 offset:0x2c00
	s_waitcnt lgkmcnt(6)
	v_mfma_f32_32x32x16_bf16 v[50:65], v[148:151], v[238:241], v[50:65]
	ds_read_b64_tr_b16 v[238:239], v211 offset:0x3400
	ds_read_b64_tr_b16 v[240:241], v211 offset:0x3c00
	s_waitcnt lgkmcnt(6)
	v_mfma_f32_32x32x16_bf16 v[34:49], v[138:141], v[226:229], v[34:49]
	ds_read_b64_tr_b16 v[226:227], v211 offset:0x600
	ds_read_b64_tr_b16 v[228:229], v211 offset:0xe00
	s_waitcnt lgkmcnt(6)
	v_mfma_f32_32x32x16_bf16 v[34:49], v[222:225], v[230:233], v[34:49]
	ds_read_b64_tr_b16 v[230:231], v211 offset:0x1600
	ds_read_b64_tr_b16 v[232:233], v211 offset:0x1e00
	s_waitcnt lgkmcnt(6)
	v_mfma_f32_32x32x16_bf16 v[34:49], v[144:147], v[234:237], v[34:49]
	ds_read_b64_tr_b16 v[234:235], v211 offset:0x2600
	ds_read_b64_tr_b16 v[236:237], v211 offset:0x2e00
	s_waitcnt lgkmcnt(6)
	v_mfma_f32_32x32x16_bf16 v[34:49], v[148:151], v[238:241], v[34:49]
	ds_read_b64_tr_b16 v[238:239], v211 offset:0x3600
	ds_read_b64_tr_b16 v[240:241], v211 offset:0x3e00
	s_waitcnt lgkmcnt(6)
	v_mfma_f32_32x32x16_bf16 v[18:33], v[138:141], v[226:229], v[18:33]
	v_max_f32_e32 v138, v83, v83
	v_max_f32_e32 v139, v82, v82
	v_max_f32_e32 v138, v139, v138
	v_max3_f32 v138, v138, v84, v85
	v_max3_f32 v138, v138, v86, v87
	v_max3_f32 v138, v138, v88, v89
	v_max3_f32 v138, v138, v90, v91
	v_max3_f32 v138, v138, v92, v93
	v_max3_f32 v138, v138, v94, v95
	s_waitcnt lgkmcnt(4)
	v_mfma_f32_32x32x16_bf16 v[18:33], v[222:225], v[230:233], v[18:33]
	v_max3_f32 v138, v138, v96, v97
	v_max3_f32 v138, v138, v66, v67
	v_max3_f32 v138, v138, v68, v69
	v_max3_f32 v138, v138, v70, v71
	v_max3_f32 v138, v138, v72, v73
	v_max3_f32 v138, v138, v74, v75
	v_max3_f32 v138, v138, v76, v77
	v_max3_f32 v138, v138, v78, v79
	s_waitcnt lgkmcnt(2)
	v_mfma_f32_32x32x16_bf16 v[18:33], v[144:147], v[234:237], v[18:33]
	v_max3_f32 v138, v138, v80, v81
	v_mov_b32_e32 v139, v138
	s_nop 1
	v_permlane32_swap_b32_e32 v138, v139
	v_max_f32_e32 v139, v139, v139
	v_max_f32_e32 v138, v138, v138
	v_max_f32_e32 v138, v138, v139
	v_sub_f32_e32 v139, v138, v142
	s_mov_b32 s2, 0x42800000
	v_cmp_ge_f32_e32 vcc, s2, v139
	v_max_f32_e32 v139, v142, v142
	v_max_f32_e32 v138, v139, v138
	s_waitcnt lgkmcnt(0)
	v_mfma_f32_32x32x16_bf16 v[18:33], v[148:151], v[238:241], v[18:33]
	v_sub_f32_e32 v139, v142, v138
	v_mul_f32_e32 v139, 0x3e38aa3b, v139
	v_exp_f32_e32 v139, v139
	s_cmp_eq_u64 vcc, exec
	s_cselect_b64 s[2:3], -1, 0
	s_waitcnt vmcnt(3)
	v_cndmask_b32_e64 v222, v139, 1.0, s[2:3]
	v_cmp_gt_f32_e32 vcc, 1.0, v222
	s_waitcnt vmcnt(3)
	ds_write_b128 v214, v[122:125] offset:32768
	s_cbranch_vccz .LBB0_705
	s_and_saveexec_b64 s[4:5], s[0:1]
	ds_write_b32 v208, v222 offset:128
	s_or_b64 exec, exec, s[4:5]
	s_waitcnt lgkmcnt(0)
	v_add_u32_e32 v139, v207, v0
	ds_read_b128 v[144:147], v139 offset:224
	ds_read_b128 v[148:151], v139 offset:192
	ds_read_b128 v[224:227], v139 offset:160
	ds_read_b128 v[228:231], v139 offset:128
	s_waitcnt lgkmcnt(3)
	v_pk_mul_f32 v[14:15], v[14:15], v[144:145]
	s_waitcnt lgkmcnt(2)
	v_pk_mul_f32 v[10:11], v[10:11], v[148:149]
	s_waitcnt lgkmcnt(1)
	v_pk_mul_f32 v[6:7], v[6:7], v[224:225]
	v_pk_mul_f32 v[16:17], v[16:17], v[146:147]
	v_pk_mul_f32 v[12:13], v[12:13], v[150:151]
	v_pk_mul_f32 v[8:9], v[8:9], v[226:227]
	s_waitcnt lgkmcnt(0)
	v_pk_mul_f32 v[4:5], v[4:5], v[230:231]
	v_pk_mul_f32 v[2:3], v[2:3], v[228:229]
	v_pk_mul_f32 v[62:63], v[144:145], v[62:63]
	v_pk_mul_f32 v[58:59], v[148:149], v[58:59]
	v_pk_mul_f32 v[54:55], v[224:225], v[54:55]
	v_pk_mul_f32 v[64:65], v[146:147], v[64:65]
	v_pk_mul_f32 v[60:61], v[150:151], v[60:61]
	v_pk_mul_f32 v[56:57], v[226:227], v[56:57]
	v_pk_mul_f32 v[52:53], v[230:231], v[52:53]
	v_pk_mul_f32 v[50:51], v[228:229], v[50:51]
	v_pk_mul_f32 v[46:47], v[144:145], v[46:47]
	v_pk_mul_f32 v[42:43], v[148:149], v[42:43]
	v_pk_mul_f32 v[38:39], v[224:225], v[38:39]
	v_pk_mul_f32 v[48:49], v[146:147], v[48:49]
	v_pk_mul_f32 v[44:45], v[150:151], v[44:45]
	v_pk_mul_f32 v[40:41], v[226:227], v[40:41]
	v_pk_mul_f32 v[36:37], v[230:231], v[36:37]
	v_pk_mul_f32 v[34:35], v[228:229], v[34:35]
	v_pk_mul_f32 v[30:31], v[144:145], v[30:31]
	v_pk_mul_f32 v[26:27], v[148:149], v[26:27]
	v_pk_mul_f32 v[22:23], v[224:225], v[22:23]
	v_pk_mul_f32 v[32:33], v[146:147], v[32:33]
	v_pk_mul_f32 v[28:29], v[150:151], v[28:29]
	v_pk_mul_f32 v[24:25], v[226:227], v[24:25]
	v_pk_mul_f32 v[20:21], v[230:231], v[20:21]
	v_pk_mul_f32 v[18:19], v[228:229], v[18:19]

; #define SBAR() __builtin_amdgcn_sched_barrier(0)
; template <int D0> __device__ __forceinline__ void pv_one(f32x16& od, int vb, bf16x8 pa0, bf16x8 pa1, bf16x8 pa2, bf16x8 pa3) {
;   const s16x4 l0 = tr_read<v_rd_off(D0, 0, 0)>(vb), h0 = tr_read<v_rd_off(D0, 0, 1)>(vb), l1 = tr_read<v_rd_off(D0, 1, 0)>(vb), h1 = tr_read<v_rd_off(D0, 1, 1)>(vb);
;   const s16x4 l2 = tr_read<v_rd_off(D0, 2, 0)>(vb), h2 = tr_read<v_rd_off(D0, 2, 1)>(vb), l3 = tr_read<v_rd_off(D0, 3, 0)>(vb), h3 = tr_read<v_rd_off(D0, 3, 1)>(vb);
;   asm volatile("s_waitcnt lgkmcnt(0)" ::: "memory"); SBAR();
;     ...
;   od = __builtin_amdgcn_mfma_f32_32x32x16_bf16(pa0, PK(l0, h0), od, 0, 0, 0);
;   od = __builtin_amdgcn_mfma_f32_32x32x16_bf16(pa1, PK(l1, h1), od, 0, 0, 0);
;   od = __builtin_amdgcn_mfma_f32_32x32x16_bf16(pa2, PK(l2, h2), od, 0, 0, 0);
;   od = __builtin_amdgcn_mfma_f32_32x32x16_bf16(pa3, PK(l3, h3), od, 0, 0, 0);
;     ...
; }
; __device__ __forceinline__ void pv_d0(f32x16* o, int vb, bf16x8 pa0, bf16x8 pa1, bf16x8 pa2, bf16x8 pa3) {
;   pv_one<0>(o[0], vb, pa0, pa1, pa2, pa3); pv_one<1>(o[1], vb, pa0, pa1, pa2, pa3); pv_one<2>(o[2], vb, pa0, pa1, pa2, pa3); pv_one<3>(o[3], vb, pa0, pa1, pa2, pa3);
.LBB0_707:
	ds_read_b64_tr_b16 v[226:227], v210 offset:0
	ds_read_b64_tr_b16 v[228:229], v210 offset:0x800
	ds_read_b64_tr_b16 v[230:231], v210 offset:0x1000
	ds_read_b64_tr_b16 v[232:233], v210 offset:0x1800
	ds_read_b64_tr_b16 v[234:235], v210 offset:0x2000
	ds_read_b64_tr_b16 v[236:237], v210 offset:0x2800
	ds_read_b64_tr_b16 v[238:239], v210 offset:0x3000
	ds_read_b64_tr_b16 v[240:241], v210 offset:0x3800
	s_waitcnt lgkmcnt(6)
	s_nop 0
	v_mfma_f32_32x32x16_bf16 v[2:17], v[138:141], v[226:229], v[2:17]
	ds_read_b64_tr_b16 v[226:227], v210 offset:0x200
	ds_read_b64_tr_b16 v[228:229], v210 offset:0xa00
	s_waitcnt lgkmcnt(6)
	v_mfma_f32_32x32x16_bf16 v[2:17], v[142:145], v[230:233], v[2:17]
	ds_read_b64_tr_b16 v[230:231], v210 offset:0x1200
	ds_read_b64_tr_b16 v[232:233], v210 offset:0x1a00
	s_waitcnt lgkmcnt(6)
	v_mfma_f32_32x32x16_bf16 v[2:17], v[146:149], v[234:237], v[2:17]
	ds_read_b64_tr_b16 v[234:235], v210 offset:0x2200
	ds_read_b64_tr_b16 v[236:237], v210 offset:0x2a00
	s_waitcnt lgkmcnt(6)
	v_mfma_f32_32x32x16_bf16 v[2:17], v[150:153], v[238:241], v[2:17]
	ds_read_b64_tr_b16 v[238:239], v210 offset:0x3200
	ds_read_b64_tr_b16 v[240:241], v210 offset:0x3a00
	s_waitcnt lgkmcnt(6)
	v_mfma_f32_32x32x16_bf16 v[50:65], v[138:141], v[226:229], v[50:65]
	ds_read_b64_tr_b16 v[226:227], v210 offset:0x400
	ds_read_b64_tr_b16 v[228:229], v210 offset:0xc00
	s_waitcnt lgkmcnt(6)
	v_mfma_f32_32x32x16_bf16 v[50:65], v[142:145], v[230:233], v[50:65]
	ds_read_b64_tr_b16 v[230:231], v210 offset:0x1400
	ds_read_b64_tr_b16 v[232:233], v210 offset:0x1c00
	s_waitcnt lgkmcnt(6)
	v_mfma_f32_32x32x16_bf16 v[50:65], v[146:149], v[234:237], v[50:65]
	ds_read_b64_tr_b16 v[234:235], v210 offset:0x2400
	ds_read_b64_tr_b16 v[236:237], v210 offset:0x2c00
	s_waitcnt lgkmcnt(6)
	v_mfma_f32_32x32x16_bf16 v[50:65], v[150:153], v[238:241], v[50:65]
	ds_read_b64_tr_b16 v[238:239], v210 offset:0x3400
	ds_read_b64_tr_b16 v[240:241], v210 offset:0x3c00
	s_waitcnt lgkmcnt(6)
	v_mfma_f32_32x32x16_bf16 v[34:49], v[138:141], v[226:229], v[34:49]
	ds_read_b64_tr_b16 v[226:227], v210 offset:0x600
	ds_read_b64_tr_b16 v[228:229], v210 offset:0xe00
	s_waitcnt lgkmcnt(6)
	v_mfma_f32_32x32x16_bf16 v[34:49], v[142:145], v[230:233], v[34:49]
	ds_read_b64_tr_b16 v[230:231], v210 offset:0x1600
	ds_read_b64_tr_b16 v[232:233], v210 offset:0x1e00
	s_waitcnt lgkmcnt(6)
	v_mfma_f32_32x32x16_bf16 v[34:49], v[146:149], v[234:237], v[34:49]
	ds_read_b64_tr_b16 v[234:235], v210 offset:0x2600
	ds_read_b64_tr_b16 v[236:237], v210 offset:0x2e00
	s_waitcnt lgkmcnt(6)
	v_mfma_f32_32x32x16_bf16 v[34:49], v[150:153], v[238:241], v[34:49]
	ds_read_b64_tr_b16 v[238:239], v210 offset:0x3600
	ds_read_b64_tr_b16 v[240:241], v210 offset:0x3e00
	s_waitcnt lgkmcnt(6)
	v_mfma_f32_32x32x16_bf16 v[18:33], v[138:141], v[226:229], v[18:33]
	v_max_f32_e32 v138, v83, v83
	v_max_f32_e32 v139, v82, v82
	v_max_f32_e32 v138, v139, v138
	v_max3_f32 v138, v138, v84, v85
	v_max3_f32 v138, v138, v86, v87
	v_max3_f32 v138, v138, v88, v89
	v_max3_f32 v138, v138, v90, v91
	v_max3_f32 v138, v138, v92, v93
	v_max3_f32 v138, v138, v94, v95
	s_waitcnt lgkmcnt(4)
	v_mfma_f32_32x32x16_bf16 v[18:33], v[142:145], v[230:233], v[18:33]
	v_max3_f32 v138, v138, v96, v97
	v_max3_f32 v138, v138, v66, v67
	v_max3_f32 v138, v138, v68, v69
	v_max3_f32 v138, v138, v70, v71
	v_max3_f32 v138, v138, v72, v73
	v_max3_f32 v138, v138, v74, v75
	v_max3_f32 v138, v138, v76, v77
	v_max3_f32 v138, v138, v78, v79
	s_waitcnt lgkmcnt(2)
	v_mfma_f32_32x32x16_bf16 v[18:33], v[146:149], v[234:237], v[18:33]
	v_max3_f32 v138, v138, v80, v81
	v_mov_b32_e32 v139, v138
	s_nop 1
	v_permlane32_swap_b32_e32 v138, v139
	v_max_f32_e32 v139, v139, v139
	v_max_f32_e32 v138, v138, v138
	v_max_f32_e32 v138, v138, v139
	v_sub_f32_e32 v139, v138, v223
	s_mov_b32 s2, 0x42800000
	v_cmp_ge_f32_e32 vcc, s2, v139
	v_max_f32_e32 v139, v223, v223
	v_max_f32_e32 v138, v139, v138
	s_waitcnt lgkmcnt(0)
	v_mfma_f32_32x32x16_bf16 v[18:33], v[150:153], v[238:241], v[18:33]
	v_sub_f32_e32 v139, v223, v138
	v_mul_f32_e32 v139, 0x3e38aa3b, v139
	v_exp_f32_e32 v139, v139
	s_cmp_eq_u64 vcc, exec
	s_cselect_b64 s[2:3], -1, 0
	s_waitcnt vmcnt(3)
	v_cndmask_b32_e64 v143, v139, 1.0, s[2:3]
	v_cmp_gt_f32_e32 vcc, 1.0, v143
	v_mov_b64_e32 v[182:183], v[126:127]
	v_mov_b64_e32 v[184:185], v[128:129]
	v_mov_b64_e32 v[194:195], v[130:131]
	v_mov_b64_e32 v[196:197], v[132:133]
	ds_write_b128 v214, v[134:137] offset:49152
	s_cbranch_vccz .LBB0_711
	s_and_saveexec_b64 s[6:7], s[0:1]
	ds_write_b32 v208, v143 offset:128
	s_or_b64 exec, exec, s[6:7]
	s_waitcnt lgkmcnt(0)
	v_add_u32_e32 v139, v207, v0
	ds_read_b128 v[126:129], v139 offset:224
	ds_read_b128 v[130:133], v139 offset:192
	ds_read_b128 v[134:137], v139 offset:160
	ds_read_b128 v[144:147], v139 offset:128
	s_waitcnt lgkmcnt(3)
	v_pk_mul_f32 v[14:15], v[14:15], v[126:127]
	s_waitcnt lgkmcnt(2)
	v_pk_mul_f32 v[10:11], v[10:11], v[130:131]
	s_waitcnt lgkmcnt(1)
	v_pk_mul_f32 v[6:7], v[6:7], v[134:135]
	v_pk_mul_f32 v[16:17], v[16:17], v[128:129]
	v_pk_mul_f32 v[12:13], v[12:13], v[132:133]
	v_pk_mul_f32 v[8:9], v[8:9], v[136:137]
	s_waitcnt lgkmcnt(0)
	v_pk_mul_f32 v[4:5], v[4:5], v[146:147]
	v_pk_mul_f32 v[2:3], v[2:3], v[144:145]
	v_pk_mul_f32 v[62:63], v[126:127], v[62:63]
	v_pk_mul_f32 v[58:59], v[130:131], v[58:59]
	v_pk_mul_f32 v[54:55], v[134:135], v[54:55]
	v_pk_mul_f32 v[64:65], v[128:129], v[64:65]
	v_pk_mul_f32 v[60:61], v[132:133], v[60:61]
	v_pk_mul_f32 v[56:57], v[136:137], v[56:57]
	v_pk_mul_f32 v[52:53], v[146:147], v[52:53]
	v_pk_mul_f32 v[50:51], v[144:145], v[50:51]
	v_pk_mul_f32 v[46:47], v[126:127], v[46:47]
	v_pk_mul_f32 v[42:43], v[130:131], v[42:43]
	v_pk_mul_f32 v[38:39], v[134:135], v[38:39]
	v_pk_mul_f32 v[48:49], v[128:129], v[48:49]
	v_pk_mul_f32 v[44:45], v[132:133], v[44:45]
	v_pk_mul_f32 v[40:41], v[136:137], v[40:41]
	v_pk_mul_f32 v[36:37], v[146:147], v[36:37]
	v_pk_mul_f32 v[34:35], v[144:145], v[34:35]
	v_pk_mul_f32 v[30:31], v[126:127], v[30:31]
	v_pk_mul_f32 v[26:27], v[130:131], v[26:27]
	v_pk_mul_f32 v[22:23], v[134:135], v[22:23]
	v_pk_mul_f32 v[32:33], v[128:129], v[32:33]
	v_pk_mul_f32 v[28:29], v[132:133], v[28:29]
	v_pk_mul_f32 v[24:25], v[136:137], v[24:25]
	v_pk_mul_f32 v[20:21], v[146:147], v[20:21]
	v_pk_mul_f32 v[18:19], v[144:145], v[18:19]
